# PEER up: column reduction stages xor-32/xor-16 via v_permlane32/16_swap + pk_add (removes 12 cndmask + 12 ds_bpermute per token); on stack21 (no gemm_waits/l2pf)
# speedup vs baseline: 1.0080x; 1.0057x over previous
; DI void up_math(const u32x4 (&W)[16], const u32 (&pj)[16], float* __restrict__ yrow, int lane) {
;   f2 y[8];
; #pragma unroll
;   for (int i = 0; i < 8; ++i) y[i] = f2{0.f, 0.f};
; #pragma unroll
;   for (int j = 0; j < 16; ++j) {
;     const float h = __uint_as_float(pj[j] << 16);
;     const f2 hh = {h, h};
; #pragma unroll
;     for (int d = 0; d < 4; ++d) {
;       f2 lo = __builtin_amdgcn_cvt_pk_f32_fp8((int)W[j][d], false);
;       f2 hi = __builtin_amdgcn_cvt_pk_f32_fp8((int)W[j][d], true);
;       y[2 * d] = lo * hh + y[2 * d];
;       y[2 * d + 1] = hi * hh + y[2 * d + 1];
;     }
;   }
.LBB0_826:
	s_add_i32 s44, s44, 2
	s_waitcnt vmcnt(16)
	v_cvt_pk_f32_fp8_e32 v[216:217], v128
	v_cvt_pk_f32_fp8_sdwa v[226:227], v128 src0_sel:WORD_1
	v_cvt_pk_f32_fp8_e32 v[228:229], v129
	v_cvt_pk_f32_fp8_sdwa v[128:129], v129 src0_sel:WORD_1
	v_cvt_pk_f32_fp8_e32 v[230:231], v130
	v_cvt_pk_f32_fp8_sdwa v[232:233], v130 src0_sel:WORD_1
	v_cvt_pk_f32_fp8_e32 v[234:235], v131
	v_cvt_pk_f32_fp8_sdwa v[130:131], v131 src0_sel:WORD_1
	v_lshlrev_b32_e32 v132, 16, v210
	v_pk_fma_f32 v[216:217], v[132:133], v[216:217], 0 op_sel_hi:[0,1,0]
	v_pk_fma_f32 v[226:227], v[132:133], v[226:227], 0 op_sel_hi:[0,1,0]
	v_pk_fma_f32 v[228:229], v[132:133], v[228:229], 0 op_sel_hi:[0,1,0]
	v_pk_fma_f32 v[128:129], v[132:133], v[128:129], 0 op_sel_hi:[0,1,0]
	v_pk_fma_f32 v[230:231], v[132:133], v[230:231], 0 op_sel_hi:[0,1,0]
	v_pk_fma_f32 v[232:233], v[132:133], v[232:233], 0 op_sel_hi:[0,1,0]
	v_pk_fma_f32 v[234:235], v[132:133], v[234:235], 0 op_sel_hi:[0,1,0]
	v_pk_fma_f32 v[130:131], v[132:133], v[130:131], 0 op_sel_hi:[0,1,0]
	v_lshlrev_b32_e32 v132, 16, v211
	s_waitcnt vmcnt(15)
	v_cvt_pk_f32_fp8_e32 v[210:211], v124
	v_cvt_pk_f32_fp8_sdwa v[236:237], v124 src0_sel:WORD_1
	v_cvt_pk_f32_fp8_e32 v[238:239], v125
	v_cvt_pk_f32_fp8_sdwa v[124:125], v125 src0_sel:WORD_1
	v_pk_fma_f32 v[210:211], v[132:133], v[210:211], v[216:217] op_sel_hi:[0,1,1]
	v_pk_fma_f32 v[216:217], v[132:133], v[236:237], v[226:227] op_sel_hi:[0,1,1]
	v_pk_fma_f32 v[226:227], v[132:133], v[238:239], v[228:229] op_sel_hi:[0,1,1]
	v_pk_fma_f32 v[124:125], v[132:133], v[124:125], v[128:129] op_sel_hi:[0,1,1]
	v_cvt_pk_f32_fp8_e32 v[128:129], v126
	v_cvt_pk_f32_fp8_sdwa v[228:229], v126 src0_sel:WORD_1
	v_cvt_pk_f32_fp8_e32 v[236:237], v127
	v_cvt_pk_f32_fp8_sdwa v[126:127], v127 src0_sel:WORD_1
	v_pk_fma_f32 v[128:129], v[132:133], v[128:129], v[230:231] op_sel_hi:[0,1,1]
	v_pk_fma_f32 v[228:229], v[132:133], v[228:229], v[232:233] op_sel_hi:[0,1,1]
	v_pk_fma_f32 v[230:231], v[132:133], v[236:237], v[234:235] op_sel_hi:[0,1,1]
	s_waitcnt vmcnt(14)
	v_cvt_pk_f32_fp8_e32 v[232:233], v120
	v_cvt_pk_f32_fp8_sdwa v[234:235], v120 src0_sel:WORD_1
	v_cvt_pk_f32_fp8_e32 v[236:237], v121
	v_cvt_pk_f32_fp8_sdwa v[120:121], v121 src0_sel:WORD_1
	v_pk_fma_f32 v[126:127], v[132:133], v[126:127], v[130:131] op_sel_hi:[0,1,1]
	v_lshlrev_b32_e32 v130, 16, v208
	v_pk_fma_f32 v[210:211], v[130:131], v[232:233], v[210:211] op_sel_hi:[0,1,1]
	v_pk_fma_f32 v[216:217], v[130:131], v[234:235], v[216:217] op_sel_hi:[0,1,1]
	v_pk_fma_f32 v[120:121], v[130:131], v[120:121], v[124:125] op_sel_hi:[0,1,1]
	v_cvt_pk_f32_fp8_e32 v[124:125], v122
	v_cvt_pk_f32_fp8_sdwa v[232:233], v122 src0_sel:WORD_1
	v_cvt_pk_f32_fp8_e32 v[234:235], v123
	v_cvt_pk_f32_fp8_sdwa v[122:123], v123 src0_sel:WORD_1
	v_pk_fma_f32 v[226:227], v[130:131], v[236:237], v[226:227] op_sel_hi:[0,1,1]
	v_pk_fma_f32 v[124:125], v[130:131], v[124:125], v[128:129] op_sel_hi:[0,1,1]
	v_pk_fma_f32 v[128:129], v[130:131], v[232:233], v[228:229] op_sel_hi:[0,1,1]
	v_pk_fma_f32 v[228:229], v[130:131], v[234:235], v[230:231] op_sel_hi:[0,1,1]
	v_pk_fma_f32 v[122:123], v[130:131], v[122:123], v[126:127] op_sel_hi:[0,1,1]
	v_lshlrev_b32_e32 v126, 16, v209
	s_waitcnt vmcnt(13)
	v_cvt_pk_f32_fp8_e32 v[130:131], v116
	v_cvt_pk_f32_fp8_sdwa v[208:209], v116 src0_sel:WORD_1
	v_cvt_pk_f32_fp8_e32 v[230:231], v117
	v_cvt_pk_f32_fp8_sdwa v[116:117], v117 src0_sel:WORD_1
	v_pk_fma_f32 v[130:131], v[126:127], v[130:131], v[210:211] op_sel_hi:[0,1,1]
	v_pk_fma_f32 v[208:209], v[126:127], v[208:209], v[216:217] op_sel_hi:[0,1,1]
	v_pk_fma_f32 v[210:211], v[126:127], v[230:231], v[226:227] op_sel_hi:[0,1,1]
	v_pk_fma_f32 v[116:117], v[126:127], v[116:117], v[120:121] op_sel_hi:[0,1,1]
	v_cvt_pk_f32_fp8_e32 v[120:121], v118
	v_cvt_pk_f32_fp8_sdwa v[216:217], v118 src0_sel:WORD_1
	v_cvt_pk_f32_fp8_e32 v[226:227], v119
	v_cvt_pk_f32_fp8_sdwa v[118:119], v119 src0_sel:WORD_1
	v_pk_fma_f32 v[120:121], v[126:127], v[120:121], v[124:125] op_sel_hi:[0,1,1]
	v_pk_fma_f32 v[124:125], v[126:127], v[216:217], v[128:129] op_sel_hi:[0,1,1]
	v_pk_fma_f32 v[128:129], v[126:127], v[226:227], v[228:229] op_sel_hi:[0,1,1]
	v_pk_fma_f32 v[118:119], v[126:127], v[118:119], v[122:123] op_sel_hi:[0,1,1]
	s_waitcnt vmcnt(12)
	v_cvt_pk_f32_fp8_e32 v[126:127], v112
	v_cvt_pk_f32_fp8_sdwa v[216:217], v112 src0_sel:WORD_1
	v_cvt_pk_f32_fp8_e32 v[226:227], v113
	v_cvt_pk_f32_fp8_sdwa v[112:113], v113 src0_sel:WORD_1
	v_lshlrev_b32_e32 v122, 16, v206
	v_pk_fma_f32 v[126:127], v[122:123], v[126:127], v[130:131] op_sel_hi:[0,1,1]
	v_pk_fma_f32 v[130:131], v[122:123], v[216:217], v[208:209] op_sel_hi:[0,1,1]
	v_pk_fma_f32 v[208:209], v[122:123], v[226:227], v[210:211] op_sel_hi:[0,1,1]
	v_pk_fma_f32 v[112:113], v[122:123], v[112:113], v[116:117] op_sel_hi:[0,1,1]
	v_cvt_pk_f32_fp8_e32 v[116:117], v114
	v_cvt_pk_f32_fp8_sdwa v[210:211], v114 src0_sel:WORD_1
	v_cvt_pk_f32_fp8_e32 v[216:217], v115
	v_cvt_pk_f32_fp8_sdwa v[114:115], v115 src0_sel:WORD_1
	v_pk_fma_f32 v[116:117], v[122:123], v[116:117], v[120:121] op_sel_hi:[0,1,1]
	v_pk_fma_f32 v[120:121], v[122:123], v[210:211], v[124:125] op_sel_hi:[0,1,1]
	v_pk_fma_f32 v[124:125], v[122:123], v[216:217], v[128:129] op_sel_hi:[0,1,1]
	v_pk_fma_f32 v[114:115], v[122:123], v[114:115], v[118:119] op_sel_hi:[0,1,1]
	v_lshlrev_b32_e32 v118, 16, v207
	s_waitcnt vmcnt(11)
; DI void up_math(const u32x4 (&W)[16], const u32 (&pj)[16], float* __restrict__ yrow, int lane) {
;     ...
;   for (int j = 0; j < 16; ++j) {
;     const float h = __uint_as_float(pj[j] << 16);
;     const f2 hh = {h, h};
; #pragma unroll
;     for (int d = 0; d < 4; ++d) {
;       f2 lo = __builtin_amdgcn_cvt_pk_f32_fp8((int)W[j][d], false);
;       f2 hi = __builtin_amdgcn_cvt_pk_f32_fp8((int)W[j][d], true);
;       y[2 * d] = lo * hh + y[2 * d];
;       y[2 * d + 1] = hi * hh + y[2 * d + 1];
;     }
;   }
	v_cvt_pk_f32_fp8_e32 v[122:123], v108
	v_cvt_pk_f32_fp8_sdwa v[128:129], v108 src0_sel:WORD_1
	v_cvt_pk_f32_fp8_e32 v[206:207], v109
	v_cvt_pk_f32_fp8_sdwa v[108:109], v109 src0_sel:WORD_1
	v_pk_fma_f32 v[122:123], v[118:119], v[122:123], v[126:127] op_sel_hi:[0,1,1]
	v_pk_fma_f32 v[126:127], v[118:119], v[128:129], v[130:131] op_sel_hi:[0,1,1]
	v_pk_fma_f32 v[128:129], v[118:119], v[206:207], v[208:209] op_sel_hi:[0,1,1]
	v_pk_fma_f32 v[108:109], v[118:119], v[108:109], v[112:113] op_sel_hi:[0,1,1]
	v_cvt_pk_f32_fp8_e32 v[112:113], v110
	v_cvt_pk_f32_fp8_sdwa v[130:131], v110 src0_sel:WORD_1
	v_cvt_pk_f32_fp8_e32 v[206:207], v111
	v_cvt_pk_f32_fp8_sdwa v[110:111], v111 src0_sel:WORD_1
	v_pk_fma_f32 v[112:113], v[118:119], v[112:113], v[116:117] op_sel_hi:[0,1,1]
	v_pk_fma_f32 v[116:117], v[118:119], v[130:131], v[120:121] op_sel_hi:[0,1,1]
	v_pk_fma_f32 v[120:121], v[118:119], v[206:207], v[124:125] op_sel_hi:[0,1,1]
	v_pk_fma_f32 v[110:111], v[118:119], v[110:111], v[114:115] op_sel_hi:[0,1,1]
	s_waitcnt vmcnt(10)
	v_cvt_pk_f32_fp8_e32 v[118:119], v104
	v_cvt_pk_f32_fp8_sdwa v[124:125], v104 src0_sel:WORD_1
	v_cvt_pk_f32_fp8_e32 v[130:131], v105
	v_cvt_pk_f32_fp8_sdwa v[104:105], v105 src0_sel:WORD_1
	v_lshlrev_b32_e32 v114, 16, v204
	v_pk_fma_f32 v[118:119], v[114:115], v[118:119], v[122:123] op_sel_hi:[0,1,1]
	v_pk_fma_f32 v[122:123], v[114:115], v[124:125], v[126:127] op_sel_hi:[0,1,1]
	v_pk_fma_f32 v[124:125], v[114:115], v[130:131], v[128:129] op_sel_hi:[0,1,1]
	v_pk_fma_f32 v[104:105], v[114:115], v[104:105], v[108:109] op_sel_hi:[0,1,1]
	v_cvt_pk_f32_fp8_e32 v[108:109], v106
	v_cvt_pk_f32_fp8_sdwa v[126:127], v106 src0_sel:WORD_1
	v_cvt_pk_f32_fp8_e32 v[128:129], v107
	v_cvt_pk_f32_fp8_sdwa v[106:107], v107 src0_sel:WORD_1
	v_pk_fma_f32 v[108:109], v[114:115], v[108:109], v[112:113] op_sel_hi:[0,1,1]
	v_pk_fma_f32 v[112:113], v[114:115], v[126:127], v[116:117] op_sel_hi:[0,1,1]
	v_pk_fma_f32 v[116:117], v[114:115], v[128:129], v[120:121] op_sel_hi:[0,1,1]
	v_pk_fma_f32 v[106:107], v[114:115], v[106:107], v[110:111] op_sel_hi:[0,1,1]
	s_waitcnt vmcnt(9)
	v_cvt_pk_f32_fp8_e32 v[114:115], v100
	v_cvt_pk_f32_fp8_sdwa v[120:121], v100 src0_sel:WORD_1
	v_cvt_pk_f32_fp8_e32 v[126:127], v101
	v_cvt_pk_f32_fp8_sdwa v[100:101], v101 src0_sel:WORD_1
	v_lshlrev_b32_e32 v110, 16, v205
	v_pk_fma_f32 v[114:115], v[110:111], v[114:115], v[118:119] op_sel_hi:[0,1,1]
	v_pk_fma_f32 v[118:119], v[110:111], v[120:121], v[122:123] op_sel_hi:[0,1,1]
	v_pk_fma_f32 v[120:121], v[110:111], v[126:127], v[124:125] op_sel_hi:[0,1,1]
	v_pk_fma_f32 v[100:101], v[110:111], v[100:101], v[104:105] op_sel_hi:[0,1,1]
	v_cvt_pk_f32_fp8_e32 v[104:105], v102
	v_cvt_pk_f32_fp8_sdwa v[122:123], v102 src0_sel:WORD_1
	v_cvt_pk_f32_fp8_e32 v[124:125], v103
	v_cvt_pk_f32_fp8_sdwa v[102:103], v103 src0_sel:WORD_1
	v_pk_fma_f32 v[104:105], v[110:111], v[104:105], v[108:109] op_sel_hi:[0,1,1]
	v_pk_fma_f32 v[108:109], v[110:111], v[122:123], v[112:113] op_sel_hi:[0,1,1]
	v_pk_fma_f32 v[112:113], v[110:111], v[124:125], v[116:117] op_sel_hi:[0,1,1]
	v_pk_fma_f32 v[102:103], v[110:111], v[102:103], v[106:107] op_sel_hi:[0,1,1]
	s_waitcnt vmcnt(8)
	v_cvt_pk_f32_fp8_e32 v[110:111], v96
	v_cvt_pk_f32_fp8_sdwa v[116:117], v96 src0_sel:WORD_1
	v_cvt_pk_f32_fp8_e32 v[122:123], v97
	v_cvt_pk_f32_fp8_sdwa v[96:97], v97 src0_sel:WORD_1
	v_lshlrev_b32_e32 v106, 16, v202
	v_pk_fma_f32 v[110:111], v[106:107], v[110:111], v[114:115] op_sel_hi:[0,1,1]
	v_pk_fma_f32 v[114:115], v[106:107], v[116:117], v[118:119] op_sel_hi:[0,1,1]
	v_pk_fma_f32 v[116:117], v[106:107], v[122:123], v[120:121] op_sel_hi:[0,1,1]
	v_pk_fma_f32 v[96:97], v[106:107], v[96:97], v[100:101] op_sel_hi:[0,1,1]
	v_cvt_pk_f32_fp8_e32 v[100:101], v98
	v_cvt_pk_f32_fp8_sdwa v[118:119], v98 src0_sel:WORD_1
	v_cvt_pk_f32_fp8_e32 v[120:121], v99
	v_cvt_pk_f32_fp8_sdwa v[98:99], v99 src0_sel:WORD_1
	v_pk_fma_f32 v[100:101], v[106:107], v[100:101], v[104:105] op_sel_hi:[0,1,1]
	v_pk_fma_f32 v[104:105], v[106:107], v[118:119], v[108:109] op_sel_hi:[0,1,1]
	v_pk_fma_f32 v[108:109], v[106:107], v[120:121], v[112:113] op_sel_hi:[0,1,1]
	v_pk_fma_f32 v[98:99], v[106:107], v[98:99], v[102:103] op_sel_hi:[0,1,1]
	s_waitcnt vmcnt(7)
	v_cvt_pk_f32_fp8_e32 v[106:107], v92
	v_cvt_pk_f32_fp8_sdwa v[112:113], v92 src0_sel:WORD_1
	v_cvt_pk_f32_fp8_e32 v[118:119], v93
	v_cvt_pk_f32_fp8_sdwa v[92:93], v93 src0_sel:WORD_1
	v_lshlrev_b32_e32 v102, 16, v203
	v_pk_fma_f32 v[106:107], v[102:103], v[106:107], v[110:111] op_sel_hi:[0,1,1]
	v_pk_fma_f32 v[110:111], v[102:103], v[112:113], v[114:115] op_sel_hi:[0,1,1]
	v_pk_fma_f32 v[112:113], v[102:103], v[118:119], v[116:117] op_sel_hi:[0,1,1]
	v_pk_fma_f32 v[92:93], v[102:103], v[92:93], v[96:97] op_sel_hi:[0,1,1]
	v_cvt_pk_f32_fp8_e32 v[96:97], v94
	v_cvt_pk_f32_fp8_sdwa v[114:115], v94 src0_sel:WORD_1
	v_cvt_pk_f32_fp8_e32 v[116:117], v95
	v_cvt_pk_f32_fp8_sdwa v[94:95], v95 src0_sel:WORD_1
	v_pk_fma_f32 v[96:97], v[102:103], v[96:97], v[100:101] op_sel_hi:[0,1,1]
	v_pk_fma_f32 v[100:101], v[102:103], v[114:115], v[104:105] op_sel_hi:[0,1,1]
	v_pk_fma_f32 v[104:105], v[102:103], v[116:117], v[108:109] op_sel_hi:[0,1,1]
	v_pk_fma_f32 v[94:95], v[102:103], v[94:95], v[98:99] op_sel_hi:[0,1,1]
	s_waitcnt vmcnt(6)
; DI void up_math(const u32x4 (&W)[16], const u32 (&pj)[16], float* __restrict__ yrow, int lane) {
;     ...
;   for (int j = 0; j < 16; ++j) {
;     const float h = __uint_as_float(pj[j] << 16);
;     const f2 hh = {h, h};
; #pragma unroll
;     for (int d = 0; d < 4; ++d) {
;       f2 lo = __builtin_amdgcn_cvt_pk_f32_fp8((int)W[j][d], false);
;       f2 hi = __builtin_amdgcn_cvt_pk_f32_fp8((int)W[j][d], true);
;       y[2 * d] = lo * hh + y[2 * d];
;       y[2 * d + 1] = hi * hh + y[2 * d + 1];
;     }
;   }
	v_cvt_pk_f32_fp8_e32 v[102:103], v88
	v_cvt_pk_f32_fp8_sdwa v[108:109], v88 src0_sel:WORD_1
	v_cvt_pk_f32_fp8_e32 v[114:115], v89
	v_cvt_pk_f32_fp8_sdwa v[88:89], v89 src0_sel:WORD_1
	v_lshlrev_b32_e32 v98, 16, v200
	v_pk_fma_f32 v[102:103], v[98:99], v[102:103], v[106:107] op_sel_hi:[0,1,1]
	v_pk_fma_f32 v[106:107], v[98:99], v[108:109], v[110:111] op_sel_hi:[0,1,1]
	v_pk_fma_f32 v[108:109], v[98:99], v[114:115], v[112:113] op_sel_hi:[0,1,1]
	v_pk_fma_f32 v[88:89], v[98:99], v[88:89], v[92:93] op_sel_hi:[0,1,1]
	v_cvt_pk_f32_fp8_e32 v[92:93], v90
	v_cvt_pk_f32_fp8_sdwa v[110:111], v90 src0_sel:WORD_1
	v_cvt_pk_f32_fp8_e32 v[112:113], v91
	v_cvt_pk_f32_fp8_sdwa v[90:91], v91 src0_sel:WORD_1
	v_pk_fma_f32 v[92:93], v[98:99], v[92:93], v[96:97] op_sel_hi:[0,1,1]
	v_pk_fma_f32 v[96:97], v[98:99], v[110:111], v[100:101] op_sel_hi:[0,1,1]
	v_pk_fma_f32 v[100:101], v[98:99], v[112:113], v[104:105] op_sel_hi:[0,1,1]
	v_pk_fma_f32 v[90:91], v[98:99], v[90:91], v[94:95] op_sel_hi:[0,1,1]
	s_waitcnt vmcnt(5)
	v_cvt_pk_f32_fp8_e32 v[98:99], v84
	v_cvt_pk_f32_fp8_sdwa v[104:105], v84 src0_sel:WORD_1
	v_cvt_pk_f32_fp8_e32 v[110:111], v85
	v_cvt_pk_f32_fp8_sdwa v[84:85], v85 src0_sel:WORD_1
	v_lshlrev_b32_e32 v94, 16, v201
	v_pk_fma_f32 v[98:99], v[94:95], v[98:99], v[102:103] op_sel_hi:[0,1,1]
	v_pk_fma_f32 v[102:103], v[94:95], v[104:105], v[106:107] op_sel_hi:[0,1,1]
	v_pk_fma_f32 v[104:105], v[94:95], v[110:111], v[108:109] op_sel_hi:[0,1,1]
	v_pk_fma_f32 v[84:85], v[94:95], v[84:85], v[88:89] op_sel_hi:[0,1,1]
	v_cvt_pk_f32_fp8_e32 v[88:89], v86
	v_cvt_pk_f32_fp8_sdwa v[106:107], v86 src0_sel:WORD_1
	v_cvt_pk_f32_fp8_e32 v[108:109], v87
	v_cvt_pk_f32_fp8_sdwa v[86:87], v87 src0_sel:WORD_1
	v_pk_fma_f32 v[88:89], v[94:95], v[88:89], v[92:93] op_sel_hi:[0,1,1]
	v_pk_fma_f32 v[92:93], v[94:95], v[106:107], v[96:97] op_sel_hi:[0,1,1]
	v_pk_fma_f32 v[96:97], v[94:95], v[108:109], v[100:101] op_sel_hi:[0,1,1]
	v_pk_fma_f32 v[86:87], v[94:95], v[86:87], v[90:91] op_sel_hi:[0,1,1]
	s_waitcnt vmcnt(4)
	v_cvt_pk_f32_fp8_e32 v[94:95], v80
	v_cvt_pk_f32_fp8_sdwa v[100:101], v80 src0_sel:WORD_1
	v_cvt_pk_f32_fp8_e32 v[106:107], v81
	v_cvt_pk_f32_fp8_sdwa v[80:81], v81 src0_sel:WORD_1
	v_lshlrev_b32_e32 v90, 16, v198
	v_pk_fma_f32 v[94:95], v[90:91], v[94:95], v[98:99] op_sel_hi:[0,1,1]
	v_pk_fma_f32 v[98:99], v[90:91], v[100:101], v[102:103] op_sel_hi:[0,1,1]
	v_pk_fma_f32 v[100:101], v[90:91], v[106:107], v[104:105] op_sel_hi:[0,1,1]
	v_pk_fma_f32 v[80:81], v[90:91], v[80:81], v[84:85] op_sel_hi:[0,1,1]
	v_cvt_pk_f32_fp8_e32 v[84:85], v82
	v_cvt_pk_f32_fp8_sdwa v[102:103], v82 src0_sel:WORD_1
	v_cvt_pk_f32_fp8_e32 v[104:105], v83
	v_cvt_pk_f32_fp8_sdwa v[82:83], v83 src0_sel:WORD_1
	v_pk_fma_f32 v[84:85], v[90:91], v[84:85], v[88:89] op_sel_hi:[0,1,1]
	v_pk_fma_f32 v[88:89], v[90:91], v[102:103], v[92:93] op_sel_hi:[0,1,1]
	v_pk_fma_f32 v[92:93], v[90:91], v[104:105], v[96:97] op_sel_hi:[0,1,1]
	v_pk_fma_f32 v[82:83], v[90:91], v[82:83], v[86:87] op_sel_hi:[0,1,1]
	s_waitcnt vmcnt(3)
	v_cvt_pk_f32_fp8_e32 v[90:91], v76
	v_cvt_pk_f32_fp8_sdwa v[96:97], v76 src0_sel:WORD_1
	v_cvt_pk_f32_fp8_e32 v[102:103], v77
	v_cvt_pk_f32_fp8_sdwa v[76:77], v77 src0_sel:WORD_1
	v_lshlrev_b32_e32 v86, 16, v199
	v_pk_fma_f32 v[90:91], v[86:87], v[90:91], v[94:95] op_sel_hi:[0,1,1]
	v_pk_fma_f32 v[94:95], v[86:87], v[96:97], v[98:99] op_sel_hi:[0,1,1]
	v_pk_fma_f32 v[96:97], v[86:87], v[102:103], v[100:101] op_sel_hi:[0,1,1]
	v_pk_fma_f32 v[76:77], v[86:87], v[76:77], v[80:81] op_sel_hi:[0,1,1]
	v_cvt_pk_f32_fp8_e32 v[80:81], v78
	v_cvt_pk_f32_fp8_sdwa v[98:99], v78 src0_sel:WORD_1
	v_cvt_pk_f32_fp8_e32 v[100:101], v79
	v_cvt_pk_f32_fp8_sdwa v[78:79], v79 src0_sel:WORD_1
	v_pk_fma_f32 v[80:81], v[86:87], v[80:81], v[84:85] op_sel_hi:[0,1,1]
	v_pk_fma_f32 v[84:85], v[86:87], v[98:99], v[88:89] op_sel_hi:[0,1,1]
	v_pk_fma_f32 v[88:89], v[86:87], v[100:101], v[92:93] op_sel_hi:[0,1,1]
	v_pk_fma_f32 v[78:79], v[86:87], v[78:79], v[82:83] op_sel_hi:[0,1,1]
	s_waitcnt vmcnt(2)
	v_cvt_pk_f32_fp8_e32 v[86:87], v72
	v_cvt_pk_f32_fp8_sdwa v[92:93], v72 src0_sel:WORD_1
	v_cvt_pk_f32_fp8_e32 v[98:99], v73
	v_cvt_pk_f32_fp8_sdwa v[72:73], v73 src0_sel:WORD_1
	v_lshlrev_b32_e32 v82, 16, v196
	v_pk_fma_f32 v[86:87], v[82:83], v[86:87], v[90:91] op_sel_hi:[0,1,1]
	v_pk_fma_f32 v[90:91], v[82:83], v[92:93], v[94:95] op_sel_hi:[0,1,1]
	v_pk_fma_f32 v[92:93], v[82:83], v[98:99], v[96:97] op_sel_hi:[0,1,1]
	v_pk_fma_f32 v[72:73], v[82:83], v[72:73], v[76:77] op_sel_hi:[0,1,1]
	v_cvt_pk_f32_fp8_e32 v[76:77], v74
	v_cvt_pk_f32_fp8_sdwa v[94:95], v74 src0_sel:WORD_1
	v_cvt_pk_f32_fp8_e32 v[96:97], v75
	v_cvt_pk_f32_fp8_sdwa v[74:75], v75 src0_sel:WORD_1
	v_pk_fma_f32 v[76:77], v[82:83], v[76:77], v[80:81] op_sel_hi:[0,1,1]
	v_pk_fma_f32 v[80:81], v[82:83], v[94:95], v[84:85] op_sel_hi:[0,1,1]
	v_pk_fma_f32 v[84:85], v[82:83], v[96:97], v[88:89] op_sel_hi:[0,1,1]
	v_pk_fma_f32 v[74:75], v[82:83], v[74:75], v[78:79] op_sel_hi:[0,1,1]
	s_waitcnt vmcnt(1)
; DI void up_issue(u32x4 (&W)[16], u32 (&pj)[16], const u32* pl, const unsigned char* wbase, int grp) {
; #pragma unroll
;   for (int j = 0; j < 16; ++j) {
;     pj[j] = pl[8 * j + grp];
;     W[j] = *(const u32x4*)(wbase + (size_t)(pj[j] >> 16) * 1024);
;   }
; }
; DI void up_math(const u32x4 (&W)[16], const u32 (&pj)[16], float* __restrict__ yrow, int lane) {
;     ...
;   const bool b5 = lane & 32, b4 = lane & 16, b3 = lane & 8;
;   f2 q4[4];
; #pragma unroll
;   for (int i = 0; i < 4; ++i) {
;     f2 snd = b5 ? y[i] : y[i + 4]; f2 kp = b5 ? y[i + 4] : y[i];
;     q4[i] = f2{kp.x + __shfl_xor(snd.x, 32), kp.y + __shfl_xor(snd.y, 32)};
;   }
;   f2 r2[2];
; #pragma unroll
;   for (int i = 0; i < 2; ++i) {
;     f2 snd = b4 ? q4[i] : q4[i + 2]; f2 kp = b4 ? q4[i + 2] : q4[i];
;     r2[i] = f2{kp.x + __shfl_xor(snd.x, 16), kp.y + __shfl_xor(snd.y, 16)};
;   }
;   f2 a;
;   { f2 snd = b3 ? r2[0] : r2[1]; f2 kp = b3 ? r2[1] : r2[0]; a = f2{kp.x + __shfl_xor(snd.x, 8), kp.y + __shfl_xor(snd.y, 8)}; }
;   const int ci = (b5 ? 4 : 0) + (b4 ? 2 : 0) + (b3 ? 1 : 0);
;   *(float2*)(yrow + (lane & 7) * 16 + 2 * ci) = make_float2(a.x, a.y);
	v_cvt_pk_f32_fp8_e32 v[82:83], v68
	v_cvt_pk_f32_fp8_sdwa v[88:89], v68 src0_sel:WORD_1
	v_cvt_pk_f32_fp8_e32 v[94:95], v69
	v_cvt_pk_f32_fp8_sdwa v[68:69], v69 src0_sel:WORD_1
	v_lshlrev_b32_e32 v78, 16, v197
	v_pk_fma_f32 v[82:83], v[78:79], v[82:83], v[86:87] op_sel_hi:[0,1,1]
	v_pk_fma_f32 v[86:87], v[78:79], v[88:89], v[90:91] op_sel_hi:[0,1,1]
	v_pk_fma_f32 v[68:69], v[78:79], v[68:69], v[72:73] op_sel_hi:[0,1,1]
	v_cvt_pk_f32_fp8_e32 v[72:73], v70
	v_pk_fma_f32 v[88:89], v[78:79], v[94:95], v[92:93] op_sel_hi:[0,1,1]
	v_cvt_pk_f32_fp8_sdwa v[90:91], v70 src0_sel:WORD_1
	v_cvt_pk_f32_fp8_e32 v[92:93], v71
	v_cvt_pk_f32_fp8_sdwa v[70:71], v71 src0_sel:WORD_1
	v_pk_fma_f32 v[72:73], v[78:79], v[72:73], v[76:77] op_sel_hi:[0,1,1]
	v_pk_fma_f32 v[76:77], v[78:79], v[90:91], v[80:81] op_sel_hi:[0,1,1]
	v_pk_fma_f32 v[80:81], v[78:79], v[92:93], v[84:85] op_sel_hi:[0,1,1]
	v_pk_fma_f32 v[70:71], v[78:79], v[70:71], v[74:75] op_sel_hi:[0,1,1]
	s_nop 1
	v_permlane32_swap_b32_e32 v82, v72
	v_permlane32_swap_b32_e32 v83, v73
	v_permlane32_swap_b32_e32 v86, v76
	v_permlane32_swap_b32_e32 v87, v77
	v_permlane32_swap_b32_e32 v88, v80
	v_permlane32_swap_b32_e32 v89, v81
	v_permlane32_swap_b32_e32 v68, v70
	v_permlane32_swap_b32_e32 v69, v71
	v_pk_add_f32 v[72:73], v[82:83], v[72:73]
	v_pk_add_f32 v[74:75], v[86:87], v[76:77]
	v_pk_add_f32 v[76:77], v[88:89], v[80:81]
	v_pk_add_f32 v[68:69], v[68:69], v[70:71]
	s_nop 1
	v_permlane16_swap_b32_e32 v72, v76
	v_permlane16_swap_b32_e32 v73, v77
	v_permlane16_swap_b32_e32 v74, v68
	v_permlane16_swap_b32_e32 v75, v69
	v_pk_add_f32 v[70:71], v[72:73], v[76:77]
	v_pk_add_f32 v[68:69], v[74:75], v[68:69]
	s_nop 0
	v_cndmask_b32_e64 v73, v71, v69, s[14:15]
	v_cndmask_b32_e64 v72, v70, v68, s[14:15]
	ds_bpermute_b32 v72, v143, v72
	ds_bpermute_b32 v73, v143, v73
	v_cndmask_b32_e64 v69, v69, v71, s[14:15]
	v_cndmask_b32_e64 v68, v68, v70, s[14:15]
	v_add_co_u32_e32 v70, vcc, 0x1000, v188
	s_waitcnt lgkmcnt(0)
	v_pk_add_f32 v[68:69], v[68:69], v[72:73]
	v_addc_co_u32_e32 v71, vcc, 0, v189, vcc
	global_store_dwordx2 v[70:71], v[68:69], off
	v_add_u32_e32 v145, 0x400, v145
	v_lshl_add_u64 v[188:189], v[188:189], 0, s[40:41]
	s_and_b64 vcc, exec, s[28:29]
	s_cbranch_vccnz .LBB0_814
.LBB0_827:
	ds_read2_b32 v[210:211], v145 offset1:8
	ds_read2_b32 v[208:209], v145 offset0:16 offset1:24
	s_waitcnt lgkmcnt(1)
	v_lshlrev_b32_sdwa v132, v215, v210 dst_sel:DWORD dst_unused:UNUSED_PAD src0_sel:DWORD src1_sel:WORD_1
	v_lshl_add_u64 v[68:69], v[174:175], 0, v[132:133]
	v_lshlrev_b32_sdwa v132, v215, v211 dst_sel:DWORD dst_unused:UNUSED_PAD src0_sel:DWORD src1_sel:WORD_1
	v_lshl_add_u64 v[70:71], v[174:175], 0, v[132:133]
	s_waitcnt lgkmcnt(0)
	v_lshlrev_b32_sdwa v132, v215, v208 dst_sel:DWORD dst_unused:UNUSED_PAD src0_sel:DWORD src1_sel:WORD_1
	global_load_dwordx4 v[128:131], v[68:69], off
	global_load_dwordx4 v[124:127], v[70:71], off
	ds_read2_b32 v[206:207], v145 offset0:32 offset1:40
	v_lshl_add_u64 v[68:69], v[174:175], 0, v[132:133]
	v_lshlrev_b32_sdwa v132, v215, v209 dst_sel:DWORD dst_unused:UNUSED_PAD src0_sel:DWORD src1_sel:WORD_1
	v_lshl_add_u64 v[70:71], v[174:175], 0, v[132:133]
	global_load_dwordx4 v[120:123], v[68:69], off
	global_load_dwordx4 v[116:119], v[70:71], off
	ds_read2_b32 v[204:205], v145 offset0:48 offset1:56
	s_waitcnt lgkmcnt(1)
	v_lshlrev_b32_sdwa v132, v215, v206 dst_sel:DWORD dst_unused:UNUSED_PAD src0_sel:DWORD src1_sel:WORD_1
	v_lshl_add_u64 v[68:69], v[174:175], 0, v[132:133]
	v_lshlrev_b32_sdwa v132, v215, v207 dst_sel:DWORD dst_unused:UNUSED_PAD src0_sel:DWORD src1_sel:WORD_1
	v_lshl_add_u64 v[70:71], v[174:175], 0, v[132:133]
	global_load_dwordx4 v[112:115], v[68:69], off
	global_load_dwordx4 v[108:111], v[70:71], off
	s_waitcnt lgkmcnt(0)
	v_lshlrev_b32_sdwa v132, v215, v204 dst_sel:DWORD dst_unused:UNUSED_PAD src0_sel:DWORD src1_sel:WORD_1
	ds_read2_b32 v[202:203], v145 offset0:64 offset1:72
	v_lshl_add_u64 v[68:69], v[174:175], 0, v[132:133]
	v_lshlrev_b32_sdwa v132, v215, v205 dst_sel:DWORD dst_unused:UNUSED_PAD src0_sel:DWORD src1_sel:WORD_1
	v_lshl_add_u64 v[70:71], v[174:175], 0, v[132:133]
	global_load_dwordx4 v[104:107], v[68:69], off
	global_load_dwordx4 v[100:103], v[70:71], off
	ds_read2_b32 v[200:201], v145 offset0:80 offset1:88
	s_waitcnt lgkmcnt(1)
	v_lshlrev_b32_sdwa v132, v215, v202 dst_sel:DWORD dst_unused:UNUSED_PAD src0_sel:DWORD src1_sel:WORD_1
	v_lshl_add_u64 v[68:69], v[174:175], 0, v[132:133]
	v_lshlrev_b32_sdwa v132, v215, v203 dst_sel:DWORD dst_unused:UNUSED_PAD src0_sel:DWORD src1_sel:WORD_1
	v_lshl_add_u64 v[70:71], v[174:175], 0, v[132:133]
	global_load_dwordx4 v[96:99], v[68:69], off
	global_load_dwordx4 v[92:95], v[70:71], off
	s_waitcnt lgkmcnt(0)
	v_lshlrev_b32_sdwa v132, v215, v200 dst_sel:DWORD dst_unused:UNUSED_PAD src0_sel:DWORD src1_sel:WORD_1
	ds_read2_b32 v[198:199], v145 offset0:96 offset1:104
	v_lshl_add_u64 v[68:69], v[174:175], 0, v[132:133]
	v_lshlrev_b32_sdwa v132, v215, v201 dst_sel:DWORD dst_unused:UNUSED_PAD src0_sel:DWORD src1_sel:WORD_1
	v_lshl_add_u64 v[70:71], v[174:175], 0, v[132:133]
	global_load_dwordx4 v[88:91], v[68:69], off
	global_load_dwordx4 v[84:87], v[70:71], off
	ds_read2_b32 v[196:197], v145 offset0:112 offset1:120
	s_waitcnt lgkmcnt(1)
	v_lshlrev_b32_sdwa v132, v215, v198 dst_sel:DWORD dst_unused:UNUSED_PAD src0_sel:DWORD src1_sel:WORD_1
	v_lshl_add_u64 v[68:69], v[174:175], 0, v[132:133]
	v_lshlrev_b32_sdwa v132, v215, v199 dst_sel:DWORD dst_unused:UNUSED_PAD src0_sel:DWORD src1_sel:WORD_1
	v_lshl_add_u64 v[70:71], v[174:175], 0, v[132:133]
	s_waitcnt lgkmcnt(0)
; DI void up_issue(u32x4 (&W)[16], u32 (&pj)[16], const u32* pl, const unsigned char* wbase, int grp) {
; #pragma unroll
;   for (int j = 0; j < 16; ++j) {
;     pj[j] = pl[8 * j + grp];
;     W[j] = *(const u32x4*)(wbase + (size_t)(pj[j] >> 16) * 1024);
;   }
; }
; DI void up_math(const u32x4 (&W)[16], const u32 (&pj)[16], float* __restrict__ yrow, int lane) {
;   f2 y[8];
; #pragma unroll
;   for (int i = 0; i < 8; ++i) y[i] = f2{0.f, 0.f};
; #pragma unroll
;   for (int j = 0; j < 16; ++j) {
;     const float h = __uint_as_float(pj[j] << 16);
;     const f2 hh = {h, h};
; #pragma unroll
;     for (int d = 0; d < 4; ++d) {
;       f2 lo = __builtin_amdgcn_cvt_pk_f32_fp8((int)W[j][d], false);
;       f2 hi = __builtin_amdgcn_cvt_pk_f32_fp8((int)W[j][d], true);
;       y[2 * d] = lo * hh + y[2 * d];
;       y[2 * d + 1] = hi * hh + y[2 * d + 1];
;     }
;   }
	v_lshlrev_b32_sdwa v132, v215, v196 dst_sel:DWORD dst_unused:UNUSED_PAD src0_sel:DWORD src1_sel:WORD_1
	global_load_dwordx4 v[80:83], v[68:69], off
	global_load_dwordx4 v[76:79], v[70:71], off
	v_lshl_add_u64 v[68:69], v[174:175], 0, v[132:133]
	v_lshlrev_b32_sdwa v132, v215, v197 dst_sel:DWORD dst_unused:UNUSED_PAD src0_sel:DWORD src1_sel:WORD_1
	v_lshl_add_u64 v[70:71], v[174:175], 0, v[132:133]
	global_load_dwordx4 v[72:75], v[68:69], off
	s_nop 0
	global_load_dwordx4 v[68:71], v[70:71], off
	s_waitcnt vmcnt(31)
	v_cvt_pk_f32_fp8_e32 v[216:217], v4
	v_cvt_pk_f32_fp8_sdwa v[226:227], v4 src0_sel:WORD_1
	v_cvt_pk_f32_fp8_e32 v[228:229], v5
	v_cvt_pk_f32_fp8_sdwa v[230:231], v5 src0_sel:WORD_1
	v_cvt_pk_f32_fp8_e32 v[232:233], v6
	v_cvt_pk_f32_fp8_sdwa v[234:235], v6 src0_sel:WORD_1
	v_cvt_pk_f32_fp8_e32 v[236:237], v7
	v_cvt_pk_f32_fp8_sdwa v[238:239], v7 src0_sel:WORD_1
	s_waitcnt vmcnt(30)
	v_cvt_pk_f32_fp8_e32 v[240:241], v8
	v_cvt_pk_f32_fp8_sdwa v[242:243], v8 src0_sel:WORD_1
	v_cvt_pk_f32_fp8_e32 v[244:245], v9
	v_cvt_pk_f32_fp8_sdwa v[246:247], v9 src0_sel:WORD_1
	v_lshlrev_b32_e32 v132, 16, v178
	v_pk_fma_f32 v[216:217], v[132:133], v[216:217], 0 op_sel_hi:[0,1,0]
	v_pk_fma_f32 v[226:227], v[132:133], v[226:227], 0 op_sel_hi:[0,1,0]
	v_pk_fma_f32 v[228:229], v[132:133], v[228:229], 0 op_sel_hi:[0,1,0]
	v_pk_fma_f32 v[230:231], v[132:133], v[230:231], 0 op_sel_hi:[0,1,0]
	v_pk_fma_f32 v[232:233], v[132:133], v[232:233], 0 op_sel_hi:[0,1,0]
	v_pk_fma_f32 v[234:235], v[132:133], v[234:235], 0 op_sel_hi:[0,1,0]
	v_pk_fma_f32 v[236:237], v[132:133], v[236:237], 0 op_sel_hi:[0,1,0]
	v_pk_fma_f32 v[238:239], v[132:133], v[238:239], 0 op_sel_hi:[0,1,0]
	v_lshlrev_b32_e32 v132, 16, v179
	v_pk_fma_f32 v[216:217], v[132:133], v[240:241], v[216:217] op_sel_hi:[0,1,1]
	v_cvt_pk_f32_fp8_e32 v[240:241], v10
	v_pk_fma_f32 v[226:227], v[132:133], v[242:243], v[226:227] op_sel_hi:[0,1,1]
	v_pk_fma_f32 v[228:229], v[132:133], v[244:245], v[228:229] op_sel_hi:[0,1,1]
	v_pk_fma_f32 v[230:231], v[132:133], v[246:247], v[230:231] op_sel_hi:[0,1,1]
	v_cvt_pk_f32_fp8_sdwa v[242:243], v10 src0_sel:WORD_1
	v_cvt_pk_f32_fp8_e32 v[244:245], v11
	v_cvt_pk_f32_fp8_sdwa v[246:247], v11 src0_sel:WORD_1
	v_pk_fma_f32 v[232:233], v[132:133], v[240:241], v[232:233] op_sel_hi:[0,1,1]
	s_waitcnt vmcnt(29)
	v_cvt_pk_f32_fp8_e32 v[240:241], v12
	v_pk_fma_f32 v[234:235], v[132:133], v[242:243], v[234:235] op_sel_hi:[0,1,1]
	v_pk_fma_f32 v[236:237], v[132:133], v[244:245], v[236:237] op_sel_hi:[0,1,1]
	v_pk_fma_f32 v[238:239], v[132:133], v[246:247], v[238:239] op_sel_hi:[0,1,1]
	v_cvt_pk_f32_fp8_sdwa v[242:243], v12 src0_sel:WORD_1
	v_cvt_pk_f32_fp8_e32 v[244:245], v13
	v_cvt_pk_f32_fp8_sdwa v[246:247], v13 src0_sel:WORD_1
	v_lshlrev_b32_e32 v132, 16, v180
	v_pk_fma_f32 v[216:217], v[132:133], v[240:241], v[216:217] op_sel_hi:[0,1,1]
	v_cvt_pk_f32_fp8_e32 v[240:241], v14
	v_pk_fma_f32 v[226:227], v[132:133], v[242:243], v[226:227] op_sel_hi:[0,1,1]
	v_pk_fma_f32 v[228:229], v[132:133], v[244:245], v[228:229] op_sel_hi:[0,1,1]
	v_pk_fma_f32 v[230:231], v[132:133], v[246:247], v[230:231] op_sel_hi:[0,1,1]
	v_cvt_pk_f32_fp8_sdwa v[242:243], v14 src0_sel:WORD_1
	v_cvt_pk_f32_fp8_e32 v[244:245], v15
	v_cvt_pk_f32_fp8_sdwa v[246:247], v15 src0_sel:WORD_1
	v_pk_fma_f32 v[232:233], v[132:133], v[240:241], v[232:233] op_sel_hi:[0,1,1]
	s_waitcnt vmcnt(28)
	v_cvt_pk_f32_fp8_e32 v[240:241], v16
	v_pk_fma_f32 v[234:235], v[132:133], v[242:243], v[234:235] op_sel_hi:[0,1,1]
	v_pk_fma_f32 v[236:237], v[132:133], v[244:245], v[236:237] op_sel_hi:[0,1,1]
	v_pk_fma_f32 v[238:239], v[132:133], v[246:247], v[238:239] op_sel_hi:[0,1,1]
	v_cvt_pk_f32_fp8_sdwa v[242:243], v16 src0_sel:WORD_1
	v_cvt_pk_f32_fp8_e32 v[244:245], v17
	v_cvt_pk_f32_fp8_sdwa v[246:247], v17 src0_sel:WORD_1
	v_lshlrev_b32_e32 v132, 16, v181
	v_pk_fma_f32 v[216:217], v[132:133], v[240:241], v[216:217] op_sel_hi:[0,1,1]
	v_cvt_pk_f32_fp8_e32 v[240:241], v18
	v_pk_fma_f32 v[226:227], v[132:133], v[242:243], v[226:227] op_sel_hi:[0,1,1]
	v_pk_fma_f32 v[228:229], v[132:133], v[244:245], v[228:229] op_sel_hi:[0,1,1]
	v_pk_fma_f32 v[230:231], v[132:133], v[246:247], v[230:231] op_sel_hi:[0,1,1]
	v_cvt_pk_f32_fp8_sdwa v[242:243], v18 src0_sel:WORD_1
	v_cvt_pk_f32_fp8_e32 v[244:245], v19
	v_cvt_pk_f32_fp8_sdwa v[246:247], v19 src0_sel:WORD_1
	v_pk_fma_f32 v[232:233], v[132:133], v[240:241], v[232:233] op_sel_hi:[0,1,1]
	s_waitcnt vmcnt(27)
	v_cvt_pk_f32_fp8_e32 v[240:241], v20
	v_pk_fma_f32 v[234:235], v[132:133], v[242:243], v[234:235] op_sel_hi:[0,1,1]
	v_pk_fma_f32 v[236:237], v[132:133], v[244:245], v[236:237] op_sel_hi:[0,1,1]
	v_pk_fma_f32 v[238:239], v[132:133], v[246:247], v[238:239] op_sel_hi:[0,1,1]
	v_cvt_pk_f32_fp8_sdwa v[242:243], v20 src0_sel:WORD_1
	v_cvt_pk_f32_fp8_e32 v[244:245], v21
	v_cvt_pk_f32_fp8_sdwa v[246:247], v21 src0_sel:WORD_1
	v_lshlrev_b32_e32 v132, 16, v182
	v_pk_fma_f32 v[216:217], v[132:133], v[240:241], v[216:217] op_sel_hi:[0,1,1]
	v_cvt_pk_f32_fp8_e32 v[240:241], v22
	v_pk_fma_f32 v[226:227], v[132:133], v[242:243], v[226:227] op_sel_hi:[0,1,1]
	v_pk_fma_f32 v[228:229], v[132:133], v[244:245], v[228:229] op_sel_hi:[0,1,1]
	v_pk_fma_f32 v[230:231], v[132:133], v[246:247], v[230:231] op_sel_hi:[0,1,1]
	v_cvt_pk_f32_fp8_sdwa v[242:243], v22 src0_sel:WORD_1
	v_cvt_pk_f32_fp8_e32 v[244:245], v23
	v_cvt_pk_f32_fp8_sdwa v[246:247], v23 src0_sel:WORD_1
	v_pk_fma_f32 v[232:233], v[132:133], v[240:241], v[232:233] op_sel_hi:[0,1,1]
	s_waitcnt vmcnt(26)
; DI void up_math(const u32x4 (&W)[16], const u32 (&pj)[16], float* __restrict__ yrow, int lane) {
;     ...
;   for (int j = 0; j < 16; ++j) {
;     const float h = __uint_as_float(pj[j] << 16);
;     const f2 hh = {h, h};
; #pragma unroll
;     for (int d = 0; d < 4; ++d) {
;       f2 lo = __builtin_amdgcn_cvt_pk_f32_fp8((int)W[j][d], false);
;       f2 hi = __builtin_amdgcn_cvt_pk_f32_fp8((int)W[j][d], true);
;       y[2 * d] = lo * hh + y[2 * d];
;       y[2 * d + 1] = hi * hh + y[2 * d + 1];
;     }
;   }
	v_cvt_pk_f32_fp8_e32 v[240:241], v24
	v_pk_fma_f32 v[234:235], v[132:133], v[242:243], v[234:235] op_sel_hi:[0,1,1]
	v_pk_fma_f32 v[236:237], v[132:133], v[244:245], v[236:237] op_sel_hi:[0,1,1]
	v_pk_fma_f32 v[238:239], v[132:133], v[246:247], v[238:239] op_sel_hi:[0,1,1]
	v_cvt_pk_f32_fp8_sdwa v[242:243], v24 src0_sel:WORD_1
	v_cvt_pk_f32_fp8_e32 v[244:245], v25
	v_cvt_pk_f32_fp8_sdwa v[246:247], v25 src0_sel:WORD_1
	v_lshlrev_b32_e32 v132, 16, v183
	v_pk_fma_f32 v[216:217], v[132:133], v[240:241], v[216:217] op_sel_hi:[0,1,1]
	v_cvt_pk_f32_fp8_e32 v[240:241], v26
	v_pk_fma_f32 v[226:227], v[132:133], v[242:243], v[226:227] op_sel_hi:[0,1,1]
	v_pk_fma_f32 v[228:229], v[132:133], v[244:245], v[228:229] op_sel_hi:[0,1,1]
	v_pk_fma_f32 v[230:231], v[132:133], v[246:247], v[230:231] op_sel_hi:[0,1,1]
	v_cvt_pk_f32_fp8_sdwa v[242:243], v26 src0_sel:WORD_1
	v_cvt_pk_f32_fp8_e32 v[244:245], v27
	v_cvt_pk_f32_fp8_sdwa v[246:247], v27 src0_sel:WORD_1
	v_pk_fma_f32 v[232:233], v[132:133], v[240:241], v[232:233] op_sel_hi:[0,1,1]
	s_waitcnt vmcnt(25)
	v_cvt_pk_f32_fp8_e32 v[240:241], v28
	v_pk_fma_f32 v[234:235], v[132:133], v[242:243], v[234:235] op_sel_hi:[0,1,1]
	v_pk_fma_f32 v[236:237], v[132:133], v[244:245], v[236:237] op_sel_hi:[0,1,1]
	v_pk_fma_f32 v[238:239], v[132:133], v[246:247], v[238:239] op_sel_hi:[0,1,1]
	v_cvt_pk_f32_fp8_sdwa v[242:243], v28 src0_sel:WORD_1
	v_cvt_pk_f32_fp8_e32 v[244:245], v29
	v_cvt_pk_f32_fp8_sdwa v[246:247], v29 src0_sel:WORD_1
	v_lshlrev_b32_e32 v132, 16, v184
	v_pk_fma_f32 v[216:217], v[132:133], v[240:241], v[216:217] op_sel_hi:[0,1,1]
	v_cvt_pk_f32_fp8_e32 v[240:241], v30
	v_pk_fma_f32 v[226:227], v[132:133], v[242:243], v[226:227] op_sel_hi:[0,1,1]
	v_pk_fma_f32 v[228:229], v[132:133], v[244:245], v[228:229] op_sel_hi:[0,1,1]
	v_pk_fma_f32 v[230:231], v[132:133], v[246:247], v[230:231] op_sel_hi:[0,1,1]
	v_cvt_pk_f32_fp8_sdwa v[242:243], v30 src0_sel:WORD_1
	v_cvt_pk_f32_fp8_e32 v[244:245], v31
	v_cvt_pk_f32_fp8_sdwa v[246:247], v31 src0_sel:WORD_1
	v_pk_fma_f32 v[232:233], v[132:133], v[240:241], v[232:233] op_sel_hi:[0,1,1]
	s_waitcnt vmcnt(24)
	v_cvt_pk_f32_fp8_e32 v[240:241], v32
	v_pk_fma_f32 v[234:235], v[132:133], v[242:243], v[234:235] op_sel_hi:[0,1,1]
	v_pk_fma_f32 v[236:237], v[132:133], v[244:245], v[236:237] op_sel_hi:[0,1,1]
	v_pk_fma_f32 v[238:239], v[132:133], v[246:247], v[238:239] op_sel_hi:[0,1,1]
	v_cvt_pk_f32_fp8_sdwa v[242:243], v32 src0_sel:WORD_1
	v_cvt_pk_f32_fp8_e32 v[244:245], v33
	v_cvt_pk_f32_fp8_sdwa v[246:247], v33 src0_sel:WORD_1
	v_lshlrev_b32_e32 v132, 16, v185
	v_pk_fma_f32 v[216:217], v[132:133], v[240:241], v[216:217] op_sel_hi:[0,1,1]
	v_cvt_pk_f32_fp8_e32 v[240:241], v34
	v_pk_fma_f32 v[226:227], v[132:133], v[242:243], v[226:227] op_sel_hi:[0,1,1]
	v_pk_fma_f32 v[228:229], v[132:133], v[244:245], v[228:229] op_sel_hi:[0,1,1]
	v_pk_fma_f32 v[230:231], v[132:133], v[246:247], v[230:231] op_sel_hi:[0,1,1]
	v_cvt_pk_f32_fp8_sdwa v[242:243], v34 src0_sel:WORD_1
	v_cvt_pk_f32_fp8_e32 v[244:245], v35
	v_cvt_pk_f32_fp8_sdwa v[246:247], v35 src0_sel:WORD_1
	v_pk_fma_f32 v[232:233], v[132:133], v[240:241], v[232:233] op_sel_hi:[0,1,1]
	s_waitcnt vmcnt(23)
	v_cvt_pk_f32_fp8_e32 v[240:241], v36
	v_pk_fma_f32 v[234:235], v[132:133], v[242:243], v[234:235] op_sel_hi:[0,1,1]
	v_pk_fma_f32 v[236:237], v[132:133], v[244:245], v[236:237] op_sel_hi:[0,1,1]
	v_pk_fma_f32 v[238:239], v[132:133], v[246:247], v[238:239] op_sel_hi:[0,1,1]
	v_cvt_pk_f32_fp8_sdwa v[242:243], v36 src0_sel:WORD_1
	v_cvt_pk_f32_fp8_e32 v[244:245], v37
	v_cvt_pk_f32_fp8_sdwa v[246:247], v37 src0_sel:WORD_1
	v_lshlrev_b32_e32 v132, 16, v186
	v_pk_fma_f32 v[216:217], v[132:133], v[240:241], v[216:217] op_sel_hi:[0,1,1]
	v_cvt_pk_f32_fp8_e32 v[240:241], v38
	v_pk_fma_f32 v[226:227], v[132:133], v[242:243], v[226:227] op_sel_hi:[0,1,1]
	v_pk_fma_f32 v[228:229], v[132:133], v[244:245], v[228:229] op_sel_hi:[0,1,1]
	v_pk_fma_f32 v[230:231], v[132:133], v[246:247], v[230:231] op_sel_hi:[0,1,1]
	v_cvt_pk_f32_fp8_sdwa v[242:243], v38 src0_sel:WORD_1
	v_cvt_pk_f32_fp8_e32 v[244:245], v39
	v_cvt_pk_f32_fp8_sdwa v[246:247], v39 src0_sel:WORD_1
	v_pk_fma_f32 v[232:233], v[132:133], v[240:241], v[232:233] op_sel_hi:[0,1,1]
	s_waitcnt vmcnt(22)
	v_cvt_pk_f32_fp8_e32 v[240:241], v40
	v_pk_fma_f32 v[234:235], v[132:133], v[242:243], v[234:235] op_sel_hi:[0,1,1]
	v_pk_fma_f32 v[236:237], v[132:133], v[244:245], v[236:237] op_sel_hi:[0,1,1]
	v_pk_fma_f32 v[238:239], v[132:133], v[246:247], v[238:239] op_sel_hi:[0,1,1]
	v_cvt_pk_f32_fp8_sdwa v[242:243], v40 src0_sel:WORD_1
	v_cvt_pk_f32_fp8_e32 v[244:245], v41
	v_cvt_pk_f32_fp8_sdwa v[246:247], v41 src0_sel:WORD_1
	v_lshlrev_b32_e32 v132, 16, v187
	v_pk_fma_f32 v[216:217], v[132:133], v[240:241], v[216:217] op_sel_hi:[0,1,1]
	v_cvt_pk_f32_fp8_e32 v[240:241], v42
	v_pk_fma_f32 v[226:227], v[132:133], v[242:243], v[226:227] op_sel_hi:[0,1,1]
	v_pk_fma_f32 v[228:229], v[132:133], v[244:245], v[228:229] op_sel_hi:[0,1,1]
	v_pk_fma_f32 v[230:231], v[132:133], v[246:247], v[230:231] op_sel_hi:[0,1,1]
	v_cvt_pk_f32_fp8_sdwa v[242:243], v42 src0_sel:WORD_1
	v_cvt_pk_f32_fp8_e32 v[244:245], v43
	v_cvt_pk_f32_fp8_sdwa v[246:247], v43 src0_sel:WORD_1
	v_pk_fma_f32 v[232:233], v[132:133], v[240:241], v[232:233] op_sel_hi:[0,1,1]
	s_waitcnt vmcnt(21)
; DI void up_math(const u32x4 (&W)[16], const u32 (&pj)[16], float* __restrict__ yrow, int lane) {
;     ...
;   for (int j = 0; j < 16; ++j) {
;     const float h = __uint_as_float(pj[j] << 16);
;     const f2 hh = {h, h};
; #pragma unroll
;     for (int d = 0; d < 4; ++d) {
;       f2 lo = __builtin_amdgcn_cvt_pk_f32_fp8((int)W[j][d], false);
;       f2 hi = __builtin_amdgcn_cvt_pk_f32_fp8((int)W[j][d], true);
;       y[2 * d] = lo * hh + y[2 * d];
;       y[2 * d + 1] = hi * hh + y[2 * d + 1];
;     }
;   }
	v_cvt_pk_f32_fp8_e32 v[240:241], v44
	v_pk_fma_f32 v[234:235], v[132:133], v[242:243], v[234:235] op_sel_hi:[0,1,1]
	v_pk_fma_f32 v[236:237], v[132:133], v[244:245], v[236:237] op_sel_hi:[0,1,1]
	v_pk_fma_f32 v[238:239], v[132:133], v[246:247], v[238:239] op_sel_hi:[0,1,1]
	v_cvt_pk_f32_fp8_sdwa v[242:243], v44 src0_sel:WORD_1
	v_cvt_pk_f32_fp8_e32 v[244:245], v45
	v_cvt_pk_f32_fp8_sdwa v[246:247], v45 src0_sel:WORD_1
	v_lshlrev_b32_e32 v132, 16, v190
	v_pk_fma_f32 v[216:217], v[132:133], v[240:241], v[216:217] op_sel_hi:[0,1,1]
	v_cvt_pk_f32_fp8_e32 v[240:241], v46
	v_pk_fma_f32 v[226:227], v[132:133], v[242:243], v[226:227] op_sel_hi:[0,1,1]
	v_pk_fma_f32 v[228:229], v[132:133], v[244:245], v[228:229] op_sel_hi:[0,1,1]
	v_pk_fma_f32 v[230:231], v[132:133], v[246:247], v[230:231] op_sel_hi:[0,1,1]
	v_cvt_pk_f32_fp8_sdwa v[242:243], v46 src0_sel:WORD_1
	v_cvt_pk_f32_fp8_e32 v[244:245], v47
	v_cvt_pk_f32_fp8_sdwa v[246:247], v47 src0_sel:WORD_1
	v_pk_fma_f32 v[232:233], v[132:133], v[240:241], v[232:233] op_sel_hi:[0,1,1]
	s_waitcnt vmcnt(20)
	v_cvt_pk_f32_fp8_e32 v[240:241], v48
	v_pk_fma_f32 v[234:235], v[132:133], v[242:243], v[234:235] op_sel_hi:[0,1,1]
	v_pk_fma_f32 v[236:237], v[132:133], v[244:245], v[236:237] op_sel_hi:[0,1,1]
	v_pk_fma_f32 v[238:239], v[132:133], v[246:247], v[238:239] op_sel_hi:[0,1,1]
	v_cvt_pk_f32_fp8_sdwa v[242:243], v48 src0_sel:WORD_1
	v_cvt_pk_f32_fp8_e32 v[244:245], v49
	v_cvt_pk_f32_fp8_sdwa v[246:247], v49 src0_sel:WORD_1
	v_lshlrev_b32_e32 v132, 16, v191
	v_pk_fma_f32 v[216:217], v[132:133], v[240:241], v[216:217] op_sel_hi:[0,1,1]
	v_cvt_pk_f32_fp8_e32 v[240:241], v50
	v_pk_fma_f32 v[226:227], v[132:133], v[242:243], v[226:227] op_sel_hi:[0,1,1]
	v_pk_fma_f32 v[228:229], v[132:133], v[244:245], v[228:229] op_sel_hi:[0,1,1]
	v_pk_fma_f32 v[230:231], v[132:133], v[246:247], v[230:231] op_sel_hi:[0,1,1]
	v_cvt_pk_f32_fp8_sdwa v[242:243], v50 src0_sel:WORD_1
	v_cvt_pk_f32_fp8_e32 v[244:245], v51
	v_cvt_pk_f32_fp8_sdwa v[246:247], v51 src0_sel:WORD_1
	v_pk_fma_f32 v[232:233], v[132:133], v[240:241], v[232:233] op_sel_hi:[0,1,1]
	s_waitcnt vmcnt(19)
	v_cvt_pk_f32_fp8_e32 v[240:241], v52
	v_pk_fma_f32 v[234:235], v[132:133], v[242:243], v[234:235] op_sel_hi:[0,1,1]
	v_pk_fma_f32 v[236:237], v[132:133], v[244:245], v[236:237] op_sel_hi:[0,1,1]
	v_pk_fma_f32 v[238:239], v[132:133], v[246:247], v[238:239] op_sel_hi:[0,1,1]
	v_cvt_pk_f32_fp8_sdwa v[242:243], v52 src0_sel:WORD_1
	v_cvt_pk_f32_fp8_e32 v[244:245], v53
	v_cvt_pk_f32_fp8_sdwa v[246:247], v53 src0_sel:WORD_1
	v_lshlrev_b32_e32 v132, 16, v192
	v_pk_fma_f32 v[216:217], v[132:133], v[240:241], v[216:217] op_sel_hi:[0,1,1]
	v_cvt_pk_f32_fp8_e32 v[240:241], v54
	v_pk_fma_f32 v[226:227], v[132:133], v[242:243], v[226:227] op_sel_hi:[0,1,1]
	v_pk_fma_f32 v[228:229], v[132:133], v[244:245], v[228:229] op_sel_hi:[0,1,1]
	v_pk_fma_f32 v[230:231], v[132:133], v[246:247], v[230:231] op_sel_hi:[0,1,1]
	v_cvt_pk_f32_fp8_sdwa v[242:243], v54 src0_sel:WORD_1
	v_cvt_pk_f32_fp8_e32 v[244:245], v55
	v_cvt_pk_f32_fp8_sdwa v[246:247], v55 src0_sel:WORD_1
	v_pk_fma_f32 v[232:233], v[132:133], v[240:241], v[232:233] op_sel_hi:[0,1,1]
	s_waitcnt vmcnt(18)
	v_cvt_pk_f32_fp8_e32 v[240:241], v56
	v_pk_fma_f32 v[234:235], v[132:133], v[242:243], v[234:235] op_sel_hi:[0,1,1]
	v_pk_fma_f32 v[236:237], v[132:133], v[244:245], v[236:237] op_sel_hi:[0,1,1]
	v_pk_fma_f32 v[238:239], v[132:133], v[246:247], v[238:239] op_sel_hi:[0,1,1]
	v_cvt_pk_f32_fp8_sdwa v[242:243], v56 src0_sel:WORD_1
	v_cvt_pk_f32_fp8_e32 v[244:245], v57
	v_cvt_pk_f32_fp8_sdwa v[246:247], v57 src0_sel:WORD_1
	v_lshlrev_b32_e32 v132, 16, v193
	v_pk_fma_f32 v[216:217], v[132:133], v[240:241], v[216:217] op_sel_hi:[0,1,1]
	v_cvt_pk_f32_fp8_e32 v[240:241], v58
	v_pk_fma_f32 v[226:227], v[132:133], v[242:243], v[226:227] op_sel_hi:[0,1,1]
	v_pk_fma_f32 v[228:229], v[132:133], v[244:245], v[228:229] op_sel_hi:[0,1,1]
	v_pk_fma_f32 v[230:231], v[132:133], v[246:247], v[230:231] op_sel_hi:[0,1,1]
	v_cvt_pk_f32_fp8_sdwa v[242:243], v58 src0_sel:WORD_1
	v_cvt_pk_f32_fp8_e32 v[244:245], v59
	v_cvt_pk_f32_fp8_sdwa v[246:247], v59 src0_sel:WORD_1
	v_pk_fma_f32 v[232:233], v[132:133], v[240:241], v[232:233] op_sel_hi:[0,1,1]
	s_waitcnt vmcnt(17)
	v_cvt_pk_f32_fp8_e32 v[240:241], v60
	v_pk_fma_f32 v[234:235], v[132:133], v[242:243], v[234:235] op_sel_hi:[0,1,1]
	v_pk_fma_f32 v[236:237], v[132:133], v[244:245], v[236:237] op_sel_hi:[0,1,1]
	v_pk_fma_f32 v[238:239], v[132:133], v[246:247], v[238:239] op_sel_hi:[0,1,1]
	v_cvt_pk_f32_fp8_sdwa v[242:243], v60 src0_sel:WORD_1
	v_cvt_pk_f32_fp8_e32 v[244:245], v61
	v_cvt_pk_f32_fp8_sdwa v[246:247], v61 src0_sel:WORD_1
	v_lshlrev_b32_e32 v132, 16, v194
	v_pk_fma_f32 v[216:217], v[132:133], v[240:241], v[216:217] op_sel_hi:[0,1,1]
	v_cvt_pk_f32_fp8_e32 v[240:241], v62
	v_pk_fma_f32 v[226:227], v[132:133], v[242:243], v[226:227] op_sel_hi:[0,1,1]
	v_pk_fma_f32 v[228:229], v[132:133], v[244:245], v[228:229] op_sel_hi:[0,1,1]
	v_pk_fma_f32 v[230:231], v[132:133], v[246:247], v[230:231] op_sel_hi:[0,1,1]
	v_cvt_pk_f32_fp8_sdwa v[242:243], v62 src0_sel:WORD_1
	v_cvt_pk_f32_fp8_e32 v[244:245], v63
	v_cvt_pk_f32_fp8_sdwa v[246:247], v63 src0_sel:WORD_1
	v_pk_fma_f32 v[232:233], v[132:133], v[240:241], v[232:233] op_sel_hi:[0,1,1]
	s_waitcnt vmcnt(16)
; DI void up_issue(u32x4 (&W)[16], u32 (&pj)[16], const u32* pl, const unsigned char* wbase, int grp) {
; #pragma unroll
;   for (int j = 0; j < 16; ++j) {
;     pj[j] = pl[8 * j + grp];
;     W[j] = *(const u32x4*)(wbase + (size_t)(pj[j] >> 16) * 1024);
;   }
; }
; DI void up_math(const u32x4 (&W)[16], const u32 (&pj)[16], float* __restrict__ yrow, int lane) {
;     ...
;   const bool b5 = lane & 32, b4 = lane & 16, b3 = lane & 8;
;   f2 q4[4];
; #pragma unroll
;   for (int i = 0; i < 4; ++i) {
;     f2 snd = b5 ? y[i] : y[i + 4]; f2 kp = b5 ? y[i + 4] : y[i];
;     q4[i] = f2{kp.x + __shfl_xor(snd.x, 32), kp.y + __shfl_xor(snd.y, 32)};
;   }
;   f2 r2[2];
; #pragma unroll
;   for (int i = 0; i < 2; ++i) {
;     f2 snd = b4 ? q4[i] : q4[i + 2]; f2 kp = b4 ? q4[i + 2] : q4[i];
;     r2[i] = f2{kp.x + __shfl_xor(snd.x, 16), kp.y + __shfl_xor(snd.y, 16)};
;   }
;   f2 a;
;   { f2 snd = b3 ? r2[0] : r2[1]; f2 kp = b3 ? r2[1] : r2[0]; a = f2{kp.x + __shfl_xor(snd.x, 8), kp.y + __shfl_xor(snd.y, 8)}; }
;   const int ci = (b5 ? 4 : 0) + (b4 ? 2 : 0) + (b3 ? 1 : 0);
;   *(float2*)(yrow + (lane & 7) * 16 + 2 * ci) = make_float2(a.x, a.y);
	v_cvt_pk_f32_fp8_e32 v[240:241], v64
	v_pk_fma_f32 v[234:235], v[132:133], v[242:243], v[234:235] op_sel_hi:[0,1,1]
	v_pk_fma_f32 v[236:237], v[132:133], v[244:245], v[236:237] op_sel_hi:[0,1,1]
	v_pk_fma_f32 v[238:239], v[132:133], v[246:247], v[238:239] op_sel_hi:[0,1,1]
	v_cvt_pk_f32_fp8_sdwa v[242:243], v64 src0_sel:WORD_1
	v_cvt_pk_f32_fp8_e32 v[244:245], v65
	v_cvt_pk_f32_fp8_sdwa v[246:247], v65 src0_sel:WORD_1
	v_lshlrev_b32_e32 v132, 16, v195
	v_pk_fma_f32 v[216:217], v[132:133], v[240:241], v[216:217] op_sel_hi:[0,1,1]
	v_cvt_pk_f32_fp8_e32 v[240:241], v66
	v_pk_fma_f32 v[226:227], v[132:133], v[242:243], v[226:227] op_sel_hi:[0,1,1]
	v_pk_fma_f32 v[228:229], v[132:133], v[244:245], v[228:229] op_sel_hi:[0,1,1]
	v_pk_fma_f32 v[230:231], v[132:133], v[246:247], v[230:231] op_sel_hi:[0,1,1]
	v_cvt_pk_f32_fp8_sdwa v[242:243], v66 src0_sel:WORD_1
	v_cvt_pk_f32_fp8_e32 v[244:245], v67
	v_cvt_pk_f32_fp8_sdwa v[246:247], v67 src0_sel:WORD_1
	v_pk_fma_f32 v[232:233], v[132:133], v[240:241], v[232:233] op_sel_hi:[0,1,1]
	v_pk_fma_f32 v[234:235], v[132:133], v[242:243], v[234:235] op_sel_hi:[0,1,1]
	v_pk_fma_f32 v[236:237], v[132:133], v[244:245], v[236:237] op_sel_hi:[0,1,1]
	v_pk_fma_f32 v[238:239], v[132:133], v[246:247], v[238:239] op_sel_hi:[0,1,1]
	s_nop 1
	v_permlane32_swap_b32_e32 v216, v232
	v_permlane32_swap_b32_e32 v217, v233
	v_permlane32_swap_b32_e32 v228, v236
	v_permlane32_swap_b32_e32 v229, v237
	v_permlane32_swap_b32_e32 v226, v234
	v_permlane32_swap_b32_e32 v227, v235
	v_permlane32_swap_b32_e32 v230, v238
	v_permlane32_swap_b32_e32 v231, v239
	v_pk_add_f32 v[216:217], v[216:217], v[232:233]
	v_pk_add_f32 v[228:229], v[228:229], v[236:237]
	v_pk_add_f32 v[226:227], v[226:227], v[234:235]
	v_pk_add_f32 v[230:231], v[230:231], v[238:239]
	s_nop 1
	v_permlane16_swap_b32_e32 v216, v228
	v_permlane16_swap_b32_e32 v217, v229
	v_permlane16_swap_b32_e32 v226, v230
	v_permlane16_swap_b32_e32 v227, v231
	v_pk_add_f32 v[216:217], v[216:217], v[228:229]
	v_pk_add_f32 v[226:227], v[226:227], v[230:231]
	s_nop 0
	v_cndmask_b32_e64 v132, v217, v227, s[14:15]
	v_cndmask_b32_e64 v147, v216, v226, s[14:15]
	ds_bpermute_b32 v228, v143, v147
	ds_bpermute_b32 v229, v143, v132
	v_cndmask_b32_e64 v217, v227, v217, s[14:15]
	v_cndmask_b32_e64 v216, v226, v216, s[14:15]
	s_waitcnt lgkmcnt(0)
	v_pk_add_f32 v[216:217], v[216:217], v[228:229]
	global_store_dwordx2 v[188:189], v[216:217], off
	s_cmp_gt_u32 s44, 13
	s_cselect_b64 s[28:29], -1, 0
	s_and_b64 vcc, exec, s[28:29]
	s_cbranch_vccnz .LBB0_826
	ds_read2_b32 v[178:179], v145 offset0:128 offset1:136
	ds_read2_b32 v[180:181], v145 offset0:144 offset1:152
	s_waitcnt lgkmcnt(1)
	v_lshlrev_b32_sdwa v132, v215, v178 dst_sel:DWORD dst_unused:UNUSED_PAD src0_sel:DWORD src1_sel:WORD_1
	v_lshl_add_u64 v[4:5], v[174:175], 0, v[132:133]
	v_lshlrev_b32_sdwa v132, v215, v179 dst_sel:DWORD dst_unused:UNUSED_PAD src0_sel:DWORD src1_sel:WORD_1
	v_lshl_add_u64 v[8:9], v[174:175], 0, v[132:133]
	s_waitcnt lgkmcnt(0)
	v_lshlrev_b32_sdwa v132, v215, v180 dst_sel:DWORD dst_unused:UNUSED_PAD src0_sel:DWORD src1_sel:WORD_1
	global_load_dwordx4 v[4:7], v[4:5], off
	s_nop 0
	global_load_dwordx4 v[8:11], v[8:9], off
	v_lshl_add_u64 v[12:13], v[174:175], 0, v[132:133]
	ds_read2_b32 v[182:183], v145 offset0:160 offset1:168
	v_lshlrev_b32_sdwa v132, v215, v181 dst_sel:DWORD dst_unused:UNUSED_PAD src0_sel:DWORD src1_sel:WORD_1
	v_lshl_add_u64 v[16:17], v[174:175], 0, v[132:133]
	global_load_dwordx4 v[12:15], v[12:13], off
	s_nop 0
	global_load_dwordx4 v[16:19], v[16:17], off
	ds_read2_b32 v[184:185], v145 offset0:176 offset1:184
	s_waitcnt lgkmcnt(1)
	v_lshlrev_b32_sdwa v132, v215, v182 dst_sel:DWORD dst_unused:UNUSED_PAD src0_sel:DWORD src1_sel:WORD_1
	v_lshl_add_u64 v[20:21], v[174:175], 0, v[132:133]
	v_lshlrev_b32_sdwa v132, v215, v183 dst_sel:DWORD dst_unused:UNUSED_PAD src0_sel:DWORD src1_sel:WORD_1
	v_lshl_add_u64 v[24:25], v[174:175], 0, v[132:133]
	s_waitcnt lgkmcnt(0)
	v_lshlrev_b32_sdwa v132, v215, v184 dst_sel:DWORD dst_unused:UNUSED_PAD src0_sel:DWORD src1_sel:WORD_1
	global_load_dwordx4 v[20:23], v[20:21], off
	s_nop 0
	global_load_dwordx4 v[24:27], v[24:25], off
	v_lshl_add_u64 v[28:29], v[174:175], 0, v[132:133]
	ds_read2_b32 v[186:187], v145 offset0:192 offset1:200
	v_lshlrev_b32_sdwa v132, v215, v185 dst_sel:DWORD dst_unused:UNUSED_PAD src0_sel:DWORD src1_sel:WORD_1
	v_lshl_add_u64 v[32:33], v[174:175], 0, v[132:133]
	global_load_dwordx4 v[28:31], v[28:29], off
	s_nop 0
	global_load_dwordx4 v[32:35], v[32:33], off
	ds_read2_b32 v[190:191], v145 offset0:208 offset1:216
	s_waitcnt lgkmcnt(1)
	v_lshlrev_b32_sdwa v132, v215, v186 dst_sel:DWORD dst_unused:UNUSED_PAD src0_sel:DWORD src1_sel:WORD_1
	v_lshl_add_u64 v[36:37], v[174:175], 0, v[132:133]
	v_lshlrev_b32_sdwa v132, v215, v187 dst_sel:DWORD dst_unused:UNUSED_PAD src0_sel:DWORD src1_sel:WORD_1
	v_lshl_add_u64 v[40:41], v[174:175], 0, v[132:133]
	s_waitcnt lgkmcnt(0)
	v_lshlrev_b32_sdwa v132, v215, v190 dst_sel:DWORD dst_unused:UNUSED_PAD src0_sel:DWORD src1_sel:WORD_1
	global_load_dwordx4 v[36:39], v[36:37], off
	s_nop 0
	global_load_dwordx4 v[40:43], v[40:41], off
	v_lshl_add_u64 v[44:45], v[174:175], 0, v[132:133]
	ds_read2_b32 v[192:193], v145 offset0:224 offset1:232
	v_lshlrev_b32_sdwa v132, v215, v191 dst_sel:DWORD dst_unused:UNUSED_PAD src0_sel:DWORD src1_sel:WORD_1
	v_lshl_add_u64 v[48:49], v[174:175], 0, v[132:133]
	global_load_dwordx4 v[44:47], v[44:45], off
	s_nop 0
	global_load_dwordx4 v[48:51], v[48:49], off
	ds_read2_b32 v[194:195], v145 offset0:240 offset1:248
	s_waitcnt lgkmcnt(1)
	v_lshlrev_b32_sdwa v132, v215, v192 dst_sel:DWORD dst_unused:UNUSED_PAD src0_sel:DWORD src1_sel:WORD_1
	v_lshl_add_u64 v[52:53], v[174:175], 0, v[132:133]
	v_lshlrev_b32_sdwa v132, v215, v193 dst_sel:DWORD dst_unused:UNUSED_PAD src0_sel:DWORD src1_sel:WORD_1
	v_lshl_add_u64 v[56:57], v[174:175], 0, v[132:133]
	s_waitcnt lgkmcnt(0)
	v_lshlrev_b32_sdwa v132, v215, v194 dst_sel:DWORD dst_unused:UNUSED_PAD src0_sel:DWORD src1_sel:WORD_1
	v_lshl_add_u64 v[60:61], v[174:175], 0, v[132:133]
	v_lshlrev_b32_sdwa v132, v215, v195 dst_sel:DWORD dst_unused:UNUSED_PAD src0_sel:DWORD src1_sel:WORD_1
	v_lshl_add_u64 v[64:65], v[174:175], 0, v[132:133]
	global_load_dwordx4 v[52:55], v[52:53], off
	s_nop 0
	global_load_dwordx4 v[56:59], v[56:57], off
	s_nop 0
	global_load_dwordx4 v[60:63], v[60:61], off
	s_nop 0
	global_load_dwordx4 v[64:67], v[64:65], off
	s_branch .LBB0_826

; DI void up_math(const u32x4 (&W)[16], const u32 (&pj)[16], float* __restrict__ yrow, int lane) {
;   f2 y[8];
; #pragma unroll
;   for (int i = 0; i < 8; ++i) y[i] = f2{0.f, 0.f};
; #pragma unroll
;   for (int j = 0; j < 16; ++j) {
;     const float h = __uint_as_float(pj[j] << 16);
;     const f2 hh = {h, h};
; #pragma unroll
;     for (int d = 0; d < 4; ++d) {
;       f2 lo = __builtin_amdgcn_cvt_pk_f32_fp8((int)W[j][d], false);
;       f2 hi = __builtin_amdgcn_cvt_pk_f32_fp8((int)W[j][d], true);
;       y[2 * d] = lo * hh + y[2 * d];
;       y[2 * d + 1] = hi * hh + y[2 * d + 1];
;     }
;   }
.LBB0_1649:
	s_add_i32 s36, s36, 2
	s_waitcnt vmcnt(16)
	v_cvt_pk_f32_fp8_e32 v[216:217], v128
	v_cvt_pk_f32_fp8_sdwa v[226:227], v128 src0_sel:WORD_1
	v_cvt_pk_f32_fp8_e32 v[228:229], v129
	v_cvt_pk_f32_fp8_sdwa v[128:129], v129 src0_sel:WORD_1
	v_cvt_pk_f32_fp8_e32 v[230:231], v130
	v_cvt_pk_f32_fp8_sdwa v[232:233], v130 src0_sel:WORD_1
	v_cvt_pk_f32_fp8_e32 v[234:235], v131
	v_cvt_pk_f32_fp8_sdwa v[130:131], v131 src0_sel:WORD_1
	v_lshlrev_b32_e32 v132, 16, v210
	v_pk_fma_f32 v[216:217], v[132:133], v[216:217], 0 op_sel_hi:[0,1,0]
	v_pk_fma_f32 v[226:227], v[132:133], v[226:227], 0 op_sel_hi:[0,1,0]
	v_pk_fma_f32 v[228:229], v[132:133], v[228:229], 0 op_sel_hi:[0,1,0]
	v_pk_fma_f32 v[128:129], v[132:133], v[128:129], 0 op_sel_hi:[0,1,0]
	v_pk_fma_f32 v[230:231], v[132:133], v[230:231], 0 op_sel_hi:[0,1,0]
	v_pk_fma_f32 v[232:233], v[132:133], v[232:233], 0 op_sel_hi:[0,1,0]
	v_pk_fma_f32 v[234:235], v[132:133], v[234:235], 0 op_sel_hi:[0,1,0]
	v_pk_fma_f32 v[130:131], v[132:133], v[130:131], 0 op_sel_hi:[0,1,0]
	v_lshlrev_b32_e32 v132, 16, v211
	s_waitcnt vmcnt(15)
	v_cvt_pk_f32_fp8_e32 v[210:211], v124
	v_cvt_pk_f32_fp8_sdwa v[236:237], v124 src0_sel:WORD_1
	v_cvt_pk_f32_fp8_e32 v[238:239], v125
	v_cvt_pk_f32_fp8_sdwa v[124:125], v125 src0_sel:WORD_1
	v_pk_fma_f32 v[210:211], v[132:133], v[210:211], v[216:217] op_sel_hi:[0,1,1]
	v_pk_fma_f32 v[216:217], v[132:133], v[236:237], v[226:227] op_sel_hi:[0,1,1]
	v_pk_fma_f32 v[226:227], v[132:133], v[238:239], v[228:229] op_sel_hi:[0,1,1]
	v_pk_fma_f32 v[124:125], v[132:133], v[124:125], v[128:129] op_sel_hi:[0,1,1]
	v_cvt_pk_f32_fp8_e32 v[128:129], v126
	v_cvt_pk_f32_fp8_sdwa v[228:229], v126 src0_sel:WORD_1
	v_cvt_pk_f32_fp8_e32 v[236:237], v127
	v_cvt_pk_f32_fp8_sdwa v[126:127], v127 src0_sel:WORD_1
	v_pk_fma_f32 v[128:129], v[132:133], v[128:129], v[230:231] op_sel_hi:[0,1,1]
	v_pk_fma_f32 v[228:229], v[132:133], v[228:229], v[232:233] op_sel_hi:[0,1,1]
	v_pk_fma_f32 v[230:231], v[132:133], v[236:237], v[234:235] op_sel_hi:[0,1,1]
	s_waitcnt vmcnt(14)
	v_cvt_pk_f32_fp8_e32 v[232:233], v120
	v_cvt_pk_f32_fp8_sdwa v[234:235], v120 src0_sel:WORD_1
	v_cvt_pk_f32_fp8_e32 v[236:237], v121
	v_cvt_pk_f32_fp8_sdwa v[120:121], v121 src0_sel:WORD_1
	v_pk_fma_f32 v[126:127], v[132:133], v[126:127], v[130:131] op_sel_hi:[0,1,1]
	v_lshlrev_b32_e32 v130, 16, v208
	v_pk_fma_f32 v[210:211], v[130:131], v[232:233], v[210:211] op_sel_hi:[0,1,1]
	v_pk_fma_f32 v[216:217], v[130:131], v[234:235], v[216:217] op_sel_hi:[0,1,1]
	v_pk_fma_f32 v[120:121], v[130:131], v[120:121], v[124:125] op_sel_hi:[0,1,1]
	v_cvt_pk_f32_fp8_e32 v[124:125], v122
	v_cvt_pk_f32_fp8_sdwa v[232:233], v122 src0_sel:WORD_1
	v_cvt_pk_f32_fp8_e32 v[234:235], v123
	v_cvt_pk_f32_fp8_sdwa v[122:123], v123 src0_sel:WORD_1
	v_pk_fma_f32 v[226:227], v[130:131], v[236:237], v[226:227] op_sel_hi:[0,1,1]
	v_pk_fma_f32 v[124:125], v[130:131], v[124:125], v[128:129] op_sel_hi:[0,1,1]
	v_pk_fma_f32 v[128:129], v[130:131], v[232:233], v[228:229] op_sel_hi:[0,1,1]
	v_pk_fma_f32 v[228:229], v[130:131], v[234:235], v[230:231] op_sel_hi:[0,1,1]
	v_pk_fma_f32 v[122:123], v[130:131], v[122:123], v[126:127] op_sel_hi:[0,1,1]
	v_lshlrev_b32_e32 v126, 16, v209
	s_waitcnt vmcnt(13)
	v_cvt_pk_f32_fp8_e32 v[130:131], v116
	v_cvt_pk_f32_fp8_sdwa v[208:209], v116 src0_sel:WORD_1
	v_cvt_pk_f32_fp8_e32 v[230:231], v117
	v_cvt_pk_f32_fp8_sdwa v[116:117], v117 src0_sel:WORD_1
	v_pk_fma_f32 v[130:131], v[126:127], v[130:131], v[210:211] op_sel_hi:[0,1,1]
	v_pk_fma_f32 v[208:209], v[126:127], v[208:209], v[216:217] op_sel_hi:[0,1,1]
	v_pk_fma_f32 v[210:211], v[126:127], v[230:231], v[226:227] op_sel_hi:[0,1,1]
	v_pk_fma_f32 v[116:117], v[126:127], v[116:117], v[120:121] op_sel_hi:[0,1,1]
	v_cvt_pk_f32_fp8_e32 v[120:121], v118
	v_cvt_pk_f32_fp8_sdwa v[216:217], v118 src0_sel:WORD_1
	v_cvt_pk_f32_fp8_e32 v[226:227], v119
	v_cvt_pk_f32_fp8_sdwa v[118:119], v119 src0_sel:WORD_1
	v_pk_fma_f32 v[120:121], v[126:127], v[120:121], v[124:125] op_sel_hi:[0,1,1]
	v_pk_fma_f32 v[124:125], v[126:127], v[216:217], v[128:129] op_sel_hi:[0,1,1]
	v_pk_fma_f32 v[128:129], v[126:127], v[226:227], v[228:229] op_sel_hi:[0,1,1]
	v_pk_fma_f32 v[118:119], v[126:127], v[118:119], v[122:123] op_sel_hi:[0,1,1]
	s_waitcnt vmcnt(12)
	v_cvt_pk_f32_fp8_e32 v[126:127], v112
	v_cvt_pk_f32_fp8_sdwa v[216:217], v112 src0_sel:WORD_1
	v_cvt_pk_f32_fp8_e32 v[226:227], v113
	v_cvt_pk_f32_fp8_sdwa v[112:113], v113 src0_sel:WORD_1
	v_lshlrev_b32_e32 v122, 16, v206
	v_pk_fma_f32 v[126:127], v[122:123], v[126:127], v[130:131] op_sel_hi:[0,1,1]
	v_pk_fma_f32 v[130:131], v[122:123], v[216:217], v[208:209] op_sel_hi:[0,1,1]
	v_pk_fma_f32 v[208:209], v[122:123], v[226:227], v[210:211] op_sel_hi:[0,1,1]
	v_pk_fma_f32 v[112:113], v[122:123], v[112:113], v[116:117] op_sel_hi:[0,1,1]
	v_cvt_pk_f32_fp8_e32 v[116:117], v114
	v_cvt_pk_f32_fp8_sdwa v[210:211], v114 src0_sel:WORD_1
	v_cvt_pk_f32_fp8_e32 v[216:217], v115
	v_cvt_pk_f32_fp8_sdwa v[114:115], v115 src0_sel:WORD_1
	v_pk_fma_f32 v[116:117], v[122:123], v[116:117], v[120:121] op_sel_hi:[0,1,1]
	v_pk_fma_f32 v[120:121], v[122:123], v[210:211], v[124:125] op_sel_hi:[0,1,1]
	v_pk_fma_f32 v[124:125], v[122:123], v[216:217], v[128:129] op_sel_hi:[0,1,1]
	v_pk_fma_f32 v[114:115], v[122:123], v[114:115], v[118:119] op_sel_hi:[0,1,1]
	v_lshlrev_b32_e32 v118, 16, v207
	s_waitcnt vmcnt(11)
; DI void up_math(const u32x4 (&W)[16], const u32 (&pj)[16], float* __restrict__ yrow, int lane) {
;     ...
;   for (int j = 0; j < 16; ++j) {
;     const float h = __uint_as_float(pj[j] << 16);
;     const f2 hh = {h, h};
; #pragma unroll
;     for (int d = 0; d < 4; ++d) {
;       f2 lo = __builtin_amdgcn_cvt_pk_f32_fp8((int)W[j][d], false);
;       f2 hi = __builtin_amdgcn_cvt_pk_f32_fp8((int)W[j][d], true);
;       y[2 * d] = lo * hh + y[2 * d];
;       y[2 * d + 1] = hi * hh + y[2 * d + 1];
;     }
;   }
	v_cvt_pk_f32_fp8_e32 v[122:123], v108
	v_cvt_pk_f32_fp8_sdwa v[128:129], v108 src0_sel:WORD_1
	v_cvt_pk_f32_fp8_e32 v[206:207], v109
	v_cvt_pk_f32_fp8_sdwa v[108:109], v109 src0_sel:WORD_1
	v_pk_fma_f32 v[122:123], v[118:119], v[122:123], v[126:127] op_sel_hi:[0,1,1]
	v_pk_fma_f32 v[126:127], v[118:119], v[128:129], v[130:131] op_sel_hi:[0,1,1]
	v_pk_fma_f32 v[128:129], v[118:119], v[206:207], v[208:209] op_sel_hi:[0,1,1]
	v_pk_fma_f32 v[108:109], v[118:119], v[108:109], v[112:113] op_sel_hi:[0,1,1]
	v_cvt_pk_f32_fp8_e32 v[112:113], v110
	v_cvt_pk_f32_fp8_sdwa v[130:131], v110 src0_sel:WORD_1
	v_cvt_pk_f32_fp8_e32 v[206:207], v111
	v_cvt_pk_f32_fp8_sdwa v[110:111], v111 src0_sel:WORD_1
	v_pk_fma_f32 v[112:113], v[118:119], v[112:113], v[116:117] op_sel_hi:[0,1,1]
	v_pk_fma_f32 v[116:117], v[118:119], v[130:131], v[120:121] op_sel_hi:[0,1,1]
	v_pk_fma_f32 v[120:121], v[118:119], v[206:207], v[124:125] op_sel_hi:[0,1,1]
	v_pk_fma_f32 v[110:111], v[118:119], v[110:111], v[114:115] op_sel_hi:[0,1,1]
	s_waitcnt vmcnt(10)
	v_cvt_pk_f32_fp8_e32 v[118:119], v104
	v_cvt_pk_f32_fp8_sdwa v[124:125], v104 src0_sel:WORD_1
	v_cvt_pk_f32_fp8_e32 v[130:131], v105
	v_cvt_pk_f32_fp8_sdwa v[104:105], v105 src0_sel:WORD_1
	v_lshlrev_b32_e32 v114, 16, v204
	v_pk_fma_f32 v[118:119], v[114:115], v[118:119], v[122:123] op_sel_hi:[0,1,1]
	v_pk_fma_f32 v[122:123], v[114:115], v[124:125], v[126:127] op_sel_hi:[0,1,1]
	v_pk_fma_f32 v[124:125], v[114:115], v[130:131], v[128:129] op_sel_hi:[0,1,1]
	v_pk_fma_f32 v[104:105], v[114:115], v[104:105], v[108:109] op_sel_hi:[0,1,1]
	v_cvt_pk_f32_fp8_e32 v[108:109], v106
	v_cvt_pk_f32_fp8_sdwa v[126:127], v106 src0_sel:WORD_1
	v_cvt_pk_f32_fp8_e32 v[128:129], v107
	v_cvt_pk_f32_fp8_sdwa v[106:107], v107 src0_sel:WORD_1
	v_pk_fma_f32 v[108:109], v[114:115], v[108:109], v[112:113] op_sel_hi:[0,1,1]
	v_pk_fma_f32 v[112:113], v[114:115], v[126:127], v[116:117] op_sel_hi:[0,1,1]
	v_pk_fma_f32 v[116:117], v[114:115], v[128:129], v[120:121] op_sel_hi:[0,1,1]
	v_pk_fma_f32 v[106:107], v[114:115], v[106:107], v[110:111] op_sel_hi:[0,1,1]
	s_waitcnt vmcnt(9)
	v_cvt_pk_f32_fp8_e32 v[114:115], v100
	v_cvt_pk_f32_fp8_sdwa v[120:121], v100 src0_sel:WORD_1
	v_cvt_pk_f32_fp8_e32 v[126:127], v101
	v_cvt_pk_f32_fp8_sdwa v[100:101], v101 src0_sel:WORD_1
	v_lshlrev_b32_e32 v110, 16, v205
	v_pk_fma_f32 v[114:115], v[110:111], v[114:115], v[118:119] op_sel_hi:[0,1,1]
	v_pk_fma_f32 v[118:119], v[110:111], v[120:121], v[122:123] op_sel_hi:[0,1,1]
	v_pk_fma_f32 v[120:121], v[110:111], v[126:127], v[124:125] op_sel_hi:[0,1,1]
	v_pk_fma_f32 v[100:101], v[110:111], v[100:101], v[104:105] op_sel_hi:[0,1,1]
	v_cvt_pk_f32_fp8_e32 v[104:105], v102
	v_cvt_pk_f32_fp8_sdwa v[122:123], v102 src0_sel:WORD_1
	v_cvt_pk_f32_fp8_e32 v[124:125], v103
	v_cvt_pk_f32_fp8_sdwa v[102:103], v103 src0_sel:WORD_1
	v_pk_fma_f32 v[104:105], v[110:111], v[104:105], v[108:109] op_sel_hi:[0,1,1]
	v_pk_fma_f32 v[108:109], v[110:111], v[122:123], v[112:113] op_sel_hi:[0,1,1]
	v_pk_fma_f32 v[112:113], v[110:111], v[124:125], v[116:117] op_sel_hi:[0,1,1]
	v_pk_fma_f32 v[102:103], v[110:111], v[102:103], v[106:107] op_sel_hi:[0,1,1]
	s_waitcnt vmcnt(8)
	v_cvt_pk_f32_fp8_e32 v[110:111], v96
	v_cvt_pk_f32_fp8_sdwa v[116:117], v96 src0_sel:WORD_1
	v_cvt_pk_f32_fp8_e32 v[122:123], v97
	v_cvt_pk_f32_fp8_sdwa v[96:97], v97 src0_sel:WORD_1
	v_lshlrev_b32_e32 v106, 16, v202
	v_pk_fma_f32 v[110:111], v[106:107], v[110:111], v[114:115] op_sel_hi:[0,1,1]
	v_pk_fma_f32 v[114:115], v[106:107], v[116:117], v[118:119] op_sel_hi:[0,1,1]
	v_pk_fma_f32 v[116:117], v[106:107], v[122:123], v[120:121] op_sel_hi:[0,1,1]
	v_pk_fma_f32 v[96:97], v[106:107], v[96:97], v[100:101] op_sel_hi:[0,1,1]
	v_cvt_pk_f32_fp8_e32 v[100:101], v98
	v_cvt_pk_f32_fp8_sdwa v[118:119], v98 src0_sel:WORD_1
	v_cvt_pk_f32_fp8_e32 v[120:121], v99
	v_cvt_pk_f32_fp8_sdwa v[98:99], v99 src0_sel:WORD_1
	v_pk_fma_f32 v[100:101], v[106:107], v[100:101], v[104:105] op_sel_hi:[0,1,1]
	v_pk_fma_f32 v[104:105], v[106:107], v[118:119], v[108:109] op_sel_hi:[0,1,1]
	v_pk_fma_f32 v[108:109], v[106:107], v[120:121], v[112:113] op_sel_hi:[0,1,1]
	v_pk_fma_f32 v[98:99], v[106:107], v[98:99], v[102:103] op_sel_hi:[0,1,1]
	s_waitcnt vmcnt(7)
	v_cvt_pk_f32_fp8_e32 v[106:107], v92
	v_cvt_pk_f32_fp8_sdwa v[112:113], v92 src0_sel:WORD_1
	v_cvt_pk_f32_fp8_e32 v[118:119], v93
	v_cvt_pk_f32_fp8_sdwa v[92:93], v93 src0_sel:WORD_1
	v_lshlrev_b32_e32 v102, 16, v203
	v_pk_fma_f32 v[106:107], v[102:103], v[106:107], v[110:111] op_sel_hi:[0,1,1]
	v_pk_fma_f32 v[110:111], v[102:103], v[112:113], v[114:115] op_sel_hi:[0,1,1]
	v_pk_fma_f32 v[112:113], v[102:103], v[118:119], v[116:117] op_sel_hi:[0,1,1]
	v_pk_fma_f32 v[92:93], v[102:103], v[92:93], v[96:97] op_sel_hi:[0,1,1]
	v_cvt_pk_f32_fp8_e32 v[96:97], v94
	v_cvt_pk_f32_fp8_sdwa v[114:115], v94 src0_sel:WORD_1
	v_cvt_pk_f32_fp8_e32 v[116:117], v95
	v_cvt_pk_f32_fp8_sdwa v[94:95], v95 src0_sel:WORD_1
	v_pk_fma_f32 v[96:97], v[102:103], v[96:97], v[100:101] op_sel_hi:[0,1,1]
	v_pk_fma_f32 v[100:101], v[102:103], v[114:115], v[104:105] op_sel_hi:[0,1,1]
	v_pk_fma_f32 v[104:105], v[102:103], v[116:117], v[108:109] op_sel_hi:[0,1,1]
	v_pk_fma_f32 v[94:95], v[102:103], v[94:95], v[98:99] op_sel_hi:[0,1,1]
	s_waitcnt vmcnt(6)
; DI void up_math(const u32x4 (&W)[16], const u32 (&pj)[16], float* __restrict__ yrow, int lane) {
;     ...
;   for (int j = 0; j < 16; ++j) {
;     const float h = __uint_as_float(pj[j] << 16);
;     const f2 hh = {h, h};
; #pragma unroll
;     for (int d = 0; d < 4; ++d) {
;       f2 lo = __builtin_amdgcn_cvt_pk_f32_fp8((int)W[j][d], false);
;       f2 hi = __builtin_amdgcn_cvt_pk_f32_fp8((int)W[j][d], true);
;       y[2 * d] = lo * hh + y[2 * d];
;       y[2 * d + 1] = hi * hh + y[2 * d + 1];
;     }
;   }
	v_cvt_pk_f32_fp8_e32 v[102:103], v88
	v_cvt_pk_f32_fp8_sdwa v[108:109], v88 src0_sel:WORD_1
	v_cvt_pk_f32_fp8_e32 v[114:115], v89
	v_cvt_pk_f32_fp8_sdwa v[88:89], v89 src0_sel:WORD_1
	v_lshlrev_b32_e32 v98, 16, v200
	v_pk_fma_f32 v[102:103], v[98:99], v[102:103], v[106:107] op_sel_hi:[0,1,1]
	v_pk_fma_f32 v[106:107], v[98:99], v[108:109], v[110:111] op_sel_hi:[0,1,1]
	v_pk_fma_f32 v[108:109], v[98:99], v[114:115], v[112:113] op_sel_hi:[0,1,1]
	v_pk_fma_f32 v[88:89], v[98:99], v[88:89], v[92:93] op_sel_hi:[0,1,1]
	v_cvt_pk_f32_fp8_e32 v[92:93], v90
	v_cvt_pk_f32_fp8_sdwa v[110:111], v90 src0_sel:WORD_1
	v_cvt_pk_f32_fp8_e32 v[112:113], v91
	v_cvt_pk_f32_fp8_sdwa v[90:91], v91 src0_sel:WORD_1
	v_pk_fma_f32 v[92:93], v[98:99], v[92:93], v[96:97] op_sel_hi:[0,1,1]
	v_pk_fma_f32 v[96:97], v[98:99], v[110:111], v[100:101] op_sel_hi:[0,1,1]
	v_pk_fma_f32 v[100:101], v[98:99], v[112:113], v[104:105] op_sel_hi:[0,1,1]
	v_pk_fma_f32 v[90:91], v[98:99], v[90:91], v[94:95] op_sel_hi:[0,1,1]
	s_waitcnt vmcnt(5)
	v_cvt_pk_f32_fp8_e32 v[98:99], v84
	v_cvt_pk_f32_fp8_sdwa v[104:105], v84 src0_sel:WORD_1
	v_cvt_pk_f32_fp8_e32 v[110:111], v85
	v_cvt_pk_f32_fp8_sdwa v[84:85], v85 src0_sel:WORD_1
	v_lshlrev_b32_e32 v94, 16, v201
	v_pk_fma_f32 v[98:99], v[94:95], v[98:99], v[102:103] op_sel_hi:[0,1,1]
	v_pk_fma_f32 v[102:103], v[94:95], v[104:105], v[106:107] op_sel_hi:[0,1,1]
	v_pk_fma_f32 v[104:105], v[94:95], v[110:111], v[108:109] op_sel_hi:[0,1,1]
	v_pk_fma_f32 v[84:85], v[94:95], v[84:85], v[88:89] op_sel_hi:[0,1,1]
	v_cvt_pk_f32_fp8_e32 v[88:89], v86
	v_cvt_pk_f32_fp8_sdwa v[106:107], v86 src0_sel:WORD_1
	v_cvt_pk_f32_fp8_e32 v[108:109], v87
	v_cvt_pk_f32_fp8_sdwa v[86:87], v87 src0_sel:WORD_1
	v_pk_fma_f32 v[88:89], v[94:95], v[88:89], v[92:93] op_sel_hi:[0,1,1]
	v_pk_fma_f32 v[92:93], v[94:95], v[106:107], v[96:97] op_sel_hi:[0,1,1]
	v_pk_fma_f32 v[96:97], v[94:95], v[108:109], v[100:101] op_sel_hi:[0,1,1]
	v_pk_fma_f32 v[86:87], v[94:95], v[86:87], v[90:91] op_sel_hi:[0,1,1]
	s_waitcnt vmcnt(4)
	v_cvt_pk_f32_fp8_e32 v[94:95], v80
	v_cvt_pk_f32_fp8_sdwa v[100:101], v80 src0_sel:WORD_1
	v_cvt_pk_f32_fp8_e32 v[106:107], v81
	v_cvt_pk_f32_fp8_sdwa v[80:81], v81 src0_sel:WORD_1
	v_lshlrev_b32_e32 v90, 16, v198
	v_pk_fma_f32 v[94:95], v[90:91], v[94:95], v[98:99] op_sel_hi:[0,1,1]
	v_pk_fma_f32 v[98:99], v[90:91], v[100:101], v[102:103] op_sel_hi:[0,1,1]
	v_pk_fma_f32 v[100:101], v[90:91], v[106:107], v[104:105] op_sel_hi:[0,1,1]
	v_pk_fma_f32 v[80:81], v[90:91], v[80:81], v[84:85] op_sel_hi:[0,1,1]
	v_cvt_pk_f32_fp8_e32 v[84:85], v82
	v_cvt_pk_f32_fp8_sdwa v[102:103], v82 src0_sel:WORD_1
	v_cvt_pk_f32_fp8_e32 v[104:105], v83
	v_cvt_pk_f32_fp8_sdwa v[82:83], v83 src0_sel:WORD_1
	v_pk_fma_f32 v[84:85], v[90:91], v[84:85], v[88:89] op_sel_hi:[0,1,1]
	v_pk_fma_f32 v[88:89], v[90:91], v[102:103], v[92:93] op_sel_hi:[0,1,1]
	v_pk_fma_f32 v[92:93], v[90:91], v[104:105], v[96:97] op_sel_hi:[0,1,1]
	v_pk_fma_f32 v[82:83], v[90:91], v[82:83], v[86:87] op_sel_hi:[0,1,1]
	s_waitcnt vmcnt(3)
	v_cvt_pk_f32_fp8_e32 v[90:91], v76
	v_cvt_pk_f32_fp8_sdwa v[96:97], v76 src0_sel:WORD_1
	v_cvt_pk_f32_fp8_e32 v[102:103], v77
	v_cvt_pk_f32_fp8_sdwa v[76:77], v77 src0_sel:WORD_1
	v_lshlrev_b32_e32 v86, 16, v199
	v_pk_fma_f32 v[90:91], v[86:87], v[90:91], v[94:95] op_sel_hi:[0,1,1]
	v_pk_fma_f32 v[94:95], v[86:87], v[96:97], v[98:99] op_sel_hi:[0,1,1]
	v_pk_fma_f32 v[96:97], v[86:87], v[102:103], v[100:101] op_sel_hi:[0,1,1]
	v_pk_fma_f32 v[76:77], v[86:87], v[76:77], v[80:81] op_sel_hi:[0,1,1]
	v_cvt_pk_f32_fp8_e32 v[80:81], v78
	v_cvt_pk_f32_fp8_sdwa v[98:99], v78 src0_sel:WORD_1
	v_cvt_pk_f32_fp8_e32 v[100:101], v79
	v_cvt_pk_f32_fp8_sdwa v[78:79], v79 src0_sel:WORD_1
	v_pk_fma_f32 v[80:81], v[86:87], v[80:81], v[84:85] op_sel_hi:[0,1,1]
	v_pk_fma_f32 v[84:85], v[86:87], v[98:99], v[88:89] op_sel_hi:[0,1,1]
	v_pk_fma_f32 v[88:89], v[86:87], v[100:101], v[92:93] op_sel_hi:[0,1,1]
	v_pk_fma_f32 v[78:79], v[86:87], v[78:79], v[82:83] op_sel_hi:[0,1,1]
	s_waitcnt vmcnt(2)
	v_cvt_pk_f32_fp8_e32 v[86:87], v72
	v_cvt_pk_f32_fp8_sdwa v[92:93], v72 src0_sel:WORD_1
	v_cvt_pk_f32_fp8_e32 v[98:99], v73
	v_cvt_pk_f32_fp8_sdwa v[72:73], v73 src0_sel:WORD_1
	v_lshlrev_b32_e32 v82, 16, v196
	v_pk_fma_f32 v[86:87], v[82:83], v[86:87], v[90:91] op_sel_hi:[0,1,1]
	v_pk_fma_f32 v[90:91], v[82:83], v[92:93], v[94:95] op_sel_hi:[0,1,1]
	v_pk_fma_f32 v[92:93], v[82:83], v[98:99], v[96:97] op_sel_hi:[0,1,1]
	v_pk_fma_f32 v[72:73], v[82:83], v[72:73], v[76:77] op_sel_hi:[0,1,1]
	v_cvt_pk_f32_fp8_e32 v[76:77], v74
	v_cvt_pk_f32_fp8_sdwa v[94:95], v74 src0_sel:WORD_1
	v_cvt_pk_f32_fp8_e32 v[96:97], v75
	v_cvt_pk_f32_fp8_sdwa v[74:75], v75 src0_sel:WORD_1
	v_pk_fma_f32 v[76:77], v[82:83], v[76:77], v[80:81] op_sel_hi:[0,1,1]
	v_pk_fma_f32 v[80:81], v[82:83], v[94:95], v[84:85] op_sel_hi:[0,1,1]
	v_pk_fma_f32 v[84:85], v[82:83], v[96:97], v[88:89] op_sel_hi:[0,1,1]
	v_pk_fma_f32 v[74:75], v[82:83], v[74:75], v[78:79] op_sel_hi:[0,1,1]
	s_waitcnt vmcnt(1)
; DI void up_issue(u32x4 (&W)[16], u32 (&pj)[16], const u32* pl, const unsigned char* wbase, int grp) {
; #pragma unroll
;   for (int j = 0; j < 16; ++j) {
;     pj[j] = pl[8 * j + grp];
;     W[j] = *(const u32x4*)(wbase + (size_t)(pj[j] >> 16) * 1024);
;   }
; }
; DI void up_math(const u32x4 (&W)[16], const u32 (&pj)[16], float* __restrict__ yrow, int lane) {
;     ...
;   const bool b5 = lane & 32, b4 = lane & 16, b3 = lane & 8;
;   f2 q4[4];
; #pragma unroll
;   for (int i = 0; i < 4; ++i) {
;     f2 snd = b5 ? y[i] : y[i + 4]; f2 kp = b5 ? y[i + 4] : y[i];
;     q4[i] = f2{kp.x + __shfl_xor(snd.x, 32), kp.y + __shfl_xor(snd.y, 32)};
;   }
;   f2 r2[2];
; #pragma unroll
;   for (int i = 0; i < 2; ++i) {
;     f2 snd = b4 ? q4[i] : q4[i + 2]; f2 kp = b4 ? q4[i + 2] : q4[i];
;     r2[i] = f2{kp.x + __shfl_xor(snd.x, 16), kp.y + __shfl_xor(snd.y, 16)};
;   }
;   f2 a;
;   { f2 snd = b3 ? r2[0] : r2[1]; f2 kp = b3 ? r2[1] : r2[0]; a = f2{kp.x + __shfl_xor(snd.x, 8), kp.y + __shfl_xor(snd.y, 8)}; }
;   const int ci = (b5 ? 4 : 0) + (b4 ? 2 : 0) + (b3 ? 1 : 0);
;   *(float2*)(yrow + (lane & 7) * 16 + 2 * ci) = make_float2(a.x, a.y);
	v_cvt_pk_f32_fp8_e32 v[82:83], v68
	v_cvt_pk_f32_fp8_sdwa v[88:89], v68 src0_sel:WORD_1
	v_cvt_pk_f32_fp8_e32 v[94:95], v69
	v_cvt_pk_f32_fp8_sdwa v[68:69], v69 src0_sel:WORD_1
	v_lshlrev_b32_e32 v78, 16, v197
	v_pk_fma_f32 v[82:83], v[78:79], v[82:83], v[86:87] op_sel_hi:[0,1,1]
	v_pk_fma_f32 v[86:87], v[78:79], v[88:89], v[90:91] op_sel_hi:[0,1,1]
	v_pk_fma_f32 v[68:69], v[78:79], v[68:69], v[72:73] op_sel_hi:[0,1,1]
	v_cvt_pk_f32_fp8_e32 v[72:73], v70
	v_pk_fma_f32 v[88:89], v[78:79], v[94:95], v[92:93] op_sel_hi:[0,1,1]
	v_cvt_pk_f32_fp8_sdwa v[90:91], v70 src0_sel:WORD_1
	v_cvt_pk_f32_fp8_e32 v[92:93], v71
	v_cvt_pk_f32_fp8_sdwa v[70:71], v71 src0_sel:WORD_1
	v_pk_fma_f32 v[72:73], v[78:79], v[72:73], v[76:77] op_sel_hi:[0,1,1]
	v_pk_fma_f32 v[76:77], v[78:79], v[90:91], v[80:81] op_sel_hi:[0,1,1]
	v_pk_fma_f32 v[80:81], v[78:79], v[92:93], v[84:85] op_sel_hi:[0,1,1]
	v_pk_fma_f32 v[70:71], v[78:79], v[70:71], v[74:75] op_sel_hi:[0,1,1]
	s_nop 1
	v_permlane32_swap_b32_e32 v82, v72
	v_permlane32_swap_b32_e32 v83, v73
	v_permlane32_swap_b32_e32 v86, v76
	v_permlane32_swap_b32_e32 v87, v77
	v_permlane32_swap_b32_e32 v88, v80
	v_permlane32_swap_b32_e32 v89, v81
	v_permlane32_swap_b32_e32 v68, v70
	v_permlane32_swap_b32_e32 v69, v71
	v_pk_add_f32 v[72:73], v[82:83], v[72:73]
	v_pk_add_f32 v[74:75], v[86:87], v[76:77]
	v_pk_add_f32 v[76:77], v[88:89], v[80:81]
	v_pk_add_f32 v[68:69], v[68:69], v[70:71]
	s_nop 1
	v_permlane16_swap_b32_e32 v72, v76
	v_permlane16_swap_b32_e32 v73, v77
	v_permlane16_swap_b32_e32 v74, v68
	v_permlane16_swap_b32_e32 v75, v69
	v_pk_add_f32 v[70:71], v[72:73], v[76:77]
	v_pk_add_f32 v[68:69], v[74:75], v[68:69]
	s_nop 0
	v_cndmask_b32_e64 v73, v71, v69, s[10:11]
	v_cndmask_b32_e64 v72, v70, v68, s[10:11]
	ds_bpermute_b32 v72, v143, v72
	ds_bpermute_b32 v73, v143, v73
	v_cndmask_b32_e64 v69, v69, v71, s[10:11]
	v_cndmask_b32_e64 v68, v68, v70, s[10:11]
	v_add_co_u32_e32 v70, vcc, 0x1000, v188
	s_waitcnt lgkmcnt(0)
	v_pk_add_f32 v[68:69], v[68:69], v[72:73]
	v_addc_co_u32_e32 v71, vcc, 0, v189, vcc
	global_store_dwordx2 v[70:71], v[68:69], off
	v_add_u32_e32 v145, 0x400, v145
	v_lshl_add_u64 v[188:189], v[188:189], 0, s[18:19]
	s_and_b64 vcc, exec, s[28:29]
	s_cbranch_vccnz .LBB0_1637
.LBB0_1650:
	ds_read2_b32 v[210:211], v145 offset1:8
	ds_read2_b32 v[208:209], v145 offset0:16 offset1:24
	s_waitcnt lgkmcnt(1)
	v_lshlrev_b32_sdwa v132, v215, v210 dst_sel:DWORD dst_unused:UNUSED_PAD src0_sel:DWORD src1_sel:WORD_1
	v_lshl_add_u64 v[68:69], v[174:175], 0, v[132:133]
	v_lshlrev_b32_sdwa v132, v215, v211 dst_sel:DWORD dst_unused:UNUSED_PAD src0_sel:DWORD src1_sel:WORD_1
	v_lshl_add_u64 v[70:71], v[174:175], 0, v[132:133]
	s_waitcnt lgkmcnt(0)
	v_lshlrev_b32_sdwa v132, v215, v208 dst_sel:DWORD dst_unused:UNUSED_PAD src0_sel:DWORD src1_sel:WORD_1
	global_load_dwordx4 v[128:131], v[68:69], off
	global_load_dwordx4 v[124:127], v[70:71], off
	ds_read2_b32 v[206:207], v145 offset0:32 offset1:40
	v_lshl_add_u64 v[68:69], v[174:175], 0, v[132:133]
	v_lshlrev_b32_sdwa v132, v215, v209 dst_sel:DWORD dst_unused:UNUSED_PAD src0_sel:DWORD src1_sel:WORD_1
	v_lshl_add_u64 v[70:71], v[174:175], 0, v[132:133]
	global_load_dwordx4 v[120:123], v[68:69], off
	global_load_dwordx4 v[116:119], v[70:71], off
	ds_read2_b32 v[204:205], v145 offset0:48 offset1:56
	s_waitcnt lgkmcnt(1)
	v_lshlrev_b32_sdwa v132, v215, v206 dst_sel:DWORD dst_unused:UNUSED_PAD src0_sel:DWORD src1_sel:WORD_1
	v_lshl_add_u64 v[68:69], v[174:175], 0, v[132:133]
	v_lshlrev_b32_sdwa v132, v215, v207 dst_sel:DWORD dst_unused:UNUSED_PAD src0_sel:DWORD src1_sel:WORD_1
	v_lshl_add_u64 v[70:71], v[174:175], 0, v[132:133]
	global_load_dwordx4 v[112:115], v[68:69], off
	global_load_dwordx4 v[108:111], v[70:71], off
	s_waitcnt lgkmcnt(0)
	v_lshlrev_b32_sdwa v132, v215, v204 dst_sel:DWORD dst_unused:UNUSED_PAD src0_sel:DWORD src1_sel:WORD_1
	ds_read2_b32 v[202:203], v145 offset0:64 offset1:72
	v_lshl_add_u64 v[68:69], v[174:175], 0, v[132:133]
	v_lshlrev_b32_sdwa v132, v215, v205 dst_sel:DWORD dst_unused:UNUSED_PAD src0_sel:DWORD src1_sel:WORD_1
	v_lshl_add_u64 v[70:71], v[174:175], 0, v[132:133]
	global_load_dwordx4 v[104:107], v[68:69], off
	global_load_dwordx4 v[100:103], v[70:71], off
	ds_read2_b32 v[200:201], v145 offset0:80 offset1:88
	s_waitcnt lgkmcnt(1)
	v_lshlrev_b32_sdwa v132, v215, v202 dst_sel:DWORD dst_unused:UNUSED_PAD src0_sel:DWORD src1_sel:WORD_1
	v_lshl_add_u64 v[68:69], v[174:175], 0, v[132:133]
	v_lshlrev_b32_sdwa v132, v215, v203 dst_sel:DWORD dst_unused:UNUSED_PAD src0_sel:DWORD src1_sel:WORD_1
	v_lshl_add_u64 v[70:71], v[174:175], 0, v[132:133]
	global_load_dwordx4 v[96:99], v[68:69], off
	global_load_dwordx4 v[92:95], v[70:71], off
	s_waitcnt lgkmcnt(0)
	v_lshlrev_b32_sdwa v132, v215, v200 dst_sel:DWORD dst_unused:UNUSED_PAD src0_sel:DWORD src1_sel:WORD_1
	ds_read2_b32 v[198:199], v145 offset0:96 offset1:104
	v_lshl_add_u64 v[68:69], v[174:175], 0, v[132:133]
	v_lshlrev_b32_sdwa v132, v215, v201 dst_sel:DWORD dst_unused:UNUSED_PAD src0_sel:DWORD src1_sel:WORD_1
	v_lshl_add_u64 v[70:71], v[174:175], 0, v[132:133]
	global_load_dwordx4 v[88:91], v[68:69], off
	global_load_dwordx4 v[84:87], v[70:71], off
	ds_read2_b32 v[196:197], v145 offset0:112 offset1:120
	s_waitcnt lgkmcnt(1)
	v_lshlrev_b32_sdwa v132, v215, v198 dst_sel:DWORD dst_unused:UNUSED_PAD src0_sel:DWORD src1_sel:WORD_1
	v_lshl_add_u64 v[68:69], v[174:175], 0, v[132:133]
	v_lshlrev_b32_sdwa v132, v215, v199 dst_sel:DWORD dst_unused:UNUSED_PAD src0_sel:DWORD src1_sel:WORD_1
	v_lshl_add_u64 v[70:71], v[174:175], 0, v[132:133]
	s_waitcnt lgkmcnt(0)
; DI void up_issue(u32x4 (&W)[16], u32 (&pj)[16], const u32* pl, const unsigned char* wbase, int grp) {
; #pragma unroll
;   for (int j = 0; j < 16; ++j) {
;     pj[j] = pl[8 * j + grp];
;     W[j] = *(const u32x4*)(wbase + (size_t)(pj[j] >> 16) * 1024);
;   }
; }
; DI void up_math(const u32x4 (&W)[16], const u32 (&pj)[16], float* __restrict__ yrow, int lane) {
;   f2 y[8];
; #pragma unroll
;   for (int i = 0; i < 8; ++i) y[i] = f2{0.f, 0.f};
; #pragma unroll
;   for (int j = 0; j < 16; ++j) {
;     const float h = __uint_as_float(pj[j] << 16);
;     const f2 hh = {h, h};
; #pragma unroll
;     for (int d = 0; d < 4; ++d) {
;       f2 lo = __builtin_amdgcn_cvt_pk_f32_fp8((int)W[j][d], false);
;       f2 hi = __builtin_amdgcn_cvt_pk_f32_fp8((int)W[j][d], true);
;       y[2 * d] = lo * hh + y[2 * d];
;       y[2 * d + 1] = hi * hh + y[2 * d + 1];
;     }
;   }
	v_lshlrev_b32_sdwa v132, v215, v196 dst_sel:DWORD dst_unused:UNUSED_PAD src0_sel:DWORD src1_sel:WORD_1
	global_load_dwordx4 v[80:83], v[68:69], off
	global_load_dwordx4 v[76:79], v[70:71], off
	v_lshl_add_u64 v[68:69], v[174:175], 0, v[132:133]
	v_lshlrev_b32_sdwa v132, v215, v197 dst_sel:DWORD dst_unused:UNUSED_PAD src0_sel:DWORD src1_sel:WORD_1
	v_lshl_add_u64 v[70:71], v[174:175], 0, v[132:133]
	global_load_dwordx4 v[72:75], v[68:69], off
	s_nop 0
	global_load_dwordx4 v[68:71], v[70:71], off
	s_waitcnt vmcnt(31)
	v_cvt_pk_f32_fp8_e32 v[216:217], v4
	v_cvt_pk_f32_fp8_sdwa v[226:227], v4 src0_sel:WORD_1
	v_cvt_pk_f32_fp8_e32 v[228:229], v5
	v_cvt_pk_f32_fp8_sdwa v[230:231], v5 src0_sel:WORD_1
	v_cvt_pk_f32_fp8_e32 v[232:233], v6
	v_cvt_pk_f32_fp8_sdwa v[234:235], v6 src0_sel:WORD_1
	v_cvt_pk_f32_fp8_e32 v[236:237], v7
	v_cvt_pk_f32_fp8_sdwa v[238:239], v7 src0_sel:WORD_1
	s_waitcnt vmcnt(30)
	v_cvt_pk_f32_fp8_e32 v[240:241], v8
	v_cvt_pk_f32_fp8_sdwa v[242:243], v8 src0_sel:WORD_1
	v_cvt_pk_f32_fp8_e32 v[244:245], v9
	v_cvt_pk_f32_fp8_sdwa v[246:247], v9 src0_sel:WORD_1
	v_lshlrev_b32_e32 v132, 16, v178
	v_pk_fma_f32 v[216:217], v[132:133], v[216:217], 0 op_sel_hi:[0,1,0]
	v_pk_fma_f32 v[226:227], v[132:133], v[226:227], 0 op_sel_hi:[0,1,0]
	v_pk_fma_f32 v[228:229], v[132:133], v[228:229], 0 op_sel_hi:[0,1,0]
	v_pk_fma_f32 v[230:231], v[132:133], v[230:231], 0 op_sel_hi:[0,1,0]
	v_pk_fma_f32 v[232:233], v[132:133], v[232:233], 0 op_sel_hi:[0,1,0]
	v_pk_fma_f32 v[234:235], v[132:133], v[234:235], 0 op_sel_hi:[0,1,0]
	v_pk_fma_f32 v[236:237], v[132:133], v[236:237], 0 op_sel_hi:[0,1,0]
	v_pk_fma_f32 v[238:239], v[132:133], v[238:239], 0 op_sel_hi:[0,1,0]
	v_lshlrev_b32_e32 v132, 16, v179
	v_pk_fma_f32 v[216:217], v[132:133], v[240:241], v[216:217] op_sel_hi:[0,1,1]
	v_cvt_pk_f32_fp8_e32 v[240:241], v10
	v_pk_fma_f32 v[226:227], v[132:133], v[242:243], v[226:227] op_sel_hi:[0,1,1]
	v_pk_fma_f32 v[228:229], v[132:133], v[244:245], v[228:229] op_sel_hi:[0,1,1]
	v_pk_fma_f32 v[230:231], v[132:133], v[246:247], v[230:231] op_sel_hi:[0,1,1]
	v_cvt_pk_f32_fp8_sdwa v[242:243], v10 src0_sel:WORD_1
	v_cvt_pk_f32_fp8_e32 v[244:245], v11
	v_cvt_pk_f32_fp8_sdwa v[246:247], v11 src0_sel:WORD_1
	v_pk_fma_f32 v[232:233], v[132:133], v[240:241], v[232:233] op_sel_hi:[0,1,1]
	s_waitcnt vmcnt(29)
	v_cvt_pk_f32_fp8_e32 v[240:241], v12
	v_pk_fma_f32 v[234:235], v[132:133], v[242:243], v[234:235] op_sel_hi:[0,1,1]
	v_pk_fma_f32 v[236:237], v[132:133], v[244:245], v[236:237] op_sel_hi:[0,1,1]
	v_pk_fma_f32 v[238:239], v[132:133], v[246:247], v[238:239] op_sel_hi:[0,1,1]
	v_cvt_pk_f32_fp8_sdwa v[242:243], v12 src0_sel:WORD_1
	v_cvt_pk_f32_fp8_e32 v[244:245], v13
	v_cvt_pk_f32_fp8_sdwa v[246:247], v13 src0_sel:WORD_1
	v_lshlrev_b32_e32 v132, 16, v180
	v_pk_fma_f32 v[216:217], v[132:133], v[240:241], v[216:217] op_sel_hi:[0,1,1]
	v_cvt_pk_f32_fp8_e32 v[240:241], v14
	v_pk_fma_f32 v[226:227], v[132:133], v[242:243], v[226:227] op_sel_hi:[0,1,1]
	v_pk_fma_f32 v[228:229], v[132:133], v[244:245], v[228:229] op_sel_hi:[0,1,1]
	v_pk_fma_f32 v[230:231], v[132:133], v[246:247], v[230:231] op_sel_hi:[0,1,1]
	v_cvt_pk_f32_fp8_sdwa v[242:243], v14 src0_sel:WORD_1
	v_cvt_pk_f32_fp8_e32 v[244:245], v15
	v_cvt_pk_f32_fp8_sdwa v[246:247], v15 src0_sel:WORD_1
	v_pk_fma_f32 v[232:233], v[132:133], v[240:241], v[232:233] op_sel_hi:[0,1,1]
	s_waitcnt vmcnt(28)
	v_cvt_pk_f32_fp8_e32 v[240:241], v16
	v_pk_fma_f32 v[234:235], v[132:133], v[242:243], v[234:235] op_sel_hi:[0,1,1]
	v_pk_fma_f32 v[236:237], v[132:133], v[244:245], v[236:237] op_sel_hi:[0,1,1]
	v_pk_fma_f32 v[238:239], v[132:133], v[246:247], v[238:239] op_sel_hi:[0,1,1]
	v_cvt_pk_f32_fp8_sdwa v[242:243], v16 src0_sel:WORD_1
	v_cvt_pk_f32_fp8_e32 v[244:245], v17
	v_cvt_pk_f32_fp8_sdwa v[246:247], v17 src0_sel:WORD_1
	v_lshlrev_b32_e32 v132, 16, v181
	v_pk_fma_f32 v[216:217], v[132:133], v[240:241], v[216:217] op_sel_hi:[0,1,1]
	v_cvt_pk_f32_fp8_e32 v[240:241], v18
	v_pk_fma_f32 v[226:227], v[132:133], v[242:243], v[226:227] op_sel_hi:[0,1,1]
	v_pk_fma_f32 v[228:229], v[132:133], v[244:245], v[228:229] op_sel_hi:[0,1,1]
	v_pk_fma_f32 v[230:231], v[132:133], v[246:247], v[230:231] op_sel_hi:[0,1,1]
	v_cvt_pk_f32_fp8_sdwa v[242:243], v18 src0_sel:WORD_1
	v_cvt_pk_f32_fp8_e32 v[244:245], v19
	v_cvt_pk_f32_fp8_sdwa v[246:247], v19 src0_sel:WORD_1
	v_pk_fma_f32 v[232:233], v[132:133], v[240:241], v[232:233] op_sel_hi:[0,1,1]
	s_waitcnt vmcnt(27)
	v_cvt_pk_f32_fp8_e32 v[240:241], v20
	v_pk_fma_f32 v[234:235], v[132:133], v[242:243], v[234:235] op_sel_hi:[0,1,1]
	v_pk_fma_f32 v[236:237], v[132:133], v[244:245], v[236:237] op_sel_hi:[0,1,1]
	v_pk_fma_f32 v[238:239], v[132:133], v[246:247], v[238:239] op_sel_hi:[0,1,1]
	v_cvt_pk_f32_fp8_sdwa v[242:243], v20 src0_sel:WORD_1
	v_cvt_pk_f32_fp8_e32 v[244:245], v21
	v_cvt_pk_f32_fp8_sdwa v[246:247], v21 src0_sel:WORD_1
	v_lshlrev_b32_e32 v132, 16, v182
	v_pk_fma_f32 v[216:217], v[132:133], v[240:241], v[216:217] op_sel_hi:[0,1,1]
	v_cvt_pk_f32_fp8_e32 v[240:241], v22
	v_pk_fma_f32 v[226:227], v[132:133], v[242:243], v[226:227] op_sel_hi:[0,1,1]
	v_pk_fma_f32 v[228:229], v[132:133], v[244:245], v[228:229] op_sel_hi:[0,1,1]
	v_pk_fma_f32 v[230:231], v[132:133], v[246:247], v[230:231] op_sel_hi:[0,1,1]
	v_cvt_pk_f32_fp8_sdwa v[242:243], v22 src0_sel:WORD_1
	v_cvt_pk_f32_fp8_e32 v[244:245], v23
	v_cvt_pk_f32_fp8_sdwa v[246:247], v23 src0_sel:WORD_1
	v_pk_fma_f32 v[232:233], v[132:133], v[240:241], v[232:233] op_sel_hi:[0,1,1]
	s_waitcnt vmcnt(26)
; DI void up_math(const u32x4 (&W)[16], const u32 (&pj)[16], float* __restrict__ yrow, int lane) {
;     ...
;   for (int j = 0; j < 16; ++j) {
;     const float h = __uint_as_float(pj[j] << 16);
;     const f2 hh = {h, h};
; #pragma unroll
;     for (int d = 0; d < 4; ++d) {
;       f2 lo = __builtin_amdgcn_cvt_pk_f32_fp8((int)W[j][d], false);
;       f2 hi = __builtin_amdgcn_cvt_pk_f32_fp8((int)W[j][d], true);
;       y[2 * d] = lo * hh + y[2 * d];
;       y[2 * d + 1] = hi * hh + y[2 * d + 1];
;     }
;   }
	v_cvt_pk_f32_fp8_e32 v[240:241], v24
	v_pk_fma_f32 v[234:235], v[132:133], v[242:243], v[234:235] op_sel_hi:[0,1,1]
	v_pk_fma_f32 v[236:237], v[132:133], v[244:245], v[236:237] op_sel_hi:[0,1,1]
	v_pk_fma_f32 v[238:239], v[132:133], v[246:247], v[238:239] op_sel_hi:[0,1,1]
	v_cvt_pk_f32_fp8_sdwa v[242:243], v24 src0_sel:WORD_1
	v_cvt_pk_f32_fp8_e32 v[244:245], v25
	v_cvt_pk_f32_fp8_sdwa v[246:247], v25 src0_sel:WORD_1
	v_lshlrev_b32_e32 v132, 16, v183
	v_pk_fma_f32 v[216:217], v[132:133], v[240:241], v[216:217] op_sel_hi:[0,1,1]
	v_cvt_pk_f32_fp8_e32 v[240:241], v26
	v_pk_fma_f32 v[226:227], v[132:133], v[242:243], v[226:227] op_sel_hi:[0,1,1]
	v_pk_fma_f32 v[228:229], v[132:133], v[244:245], v[228:229] op_sel_hi:[0,1,1]
	v_pk_fma_f32 v[230:231], v[132:133], v[246:247], v[230:231] op_sel_hi:[0,1,1]
	v_cvt_pk_f32_fp8_sdwa v[242:243], v26 src0_sel:WORD_1
	v_cvt_pk_f32_fp8_e32 v[244:245], v27
	v_cvt_pk_f32_fp8_sdwa v[246:247], v27 src0_sel:WORD_1
	v_pk_fma_f32 v[232:233], v[132:133], v[240:241], v[232:233] op_sel_hi:[0,1,1]
	s_waitcnt vmcnt(25)
	v_cvt_pk_f32_fp8_e32 v[240:241], v28
	v_pk_fma_f32 v[234:235], v[132:133], v[242:243], v[234:235] op_sel_hi:[0,1,1]
	v_pk_fma_f32 v[236:237], v[132:133], v[244:245], v[236:237] op_sel_hi:[0,1,1]
	v_pk_fma_f32 v[238:239], v[132:133], v[246:247], v[238:239] op_sel_hi:[0,1,1]
	v_cvt_pk_f32_fp8_sdwa v[242:243], v28 src0_sel:WORD_1
	v_cvt_pk_f32_fp8_e32 v[244:245], v29
	v_cvt_pk_f32_fp8_sdwa v[246:247], v29 src0_sel:WORD_1
	v_lshlrev_b32_e32 v132, 16, v184
	v_pk_fma_f32 v[216:217], v[132:133], v[240:241], v[216:217] op_sel_hi:[0,1,1]
	v_cvt_pk_f32_fp8_e32 v[240:241], v30
	v_pk_fma_f32 v[226:227], v[132:133], v[242:243], v[226:227] op_sel_hi:[0,1,1]
	v_pk_fma_f32 v[228:229], v[132:133], v[244:245], v[228:229] op_sel_hi:[0,1,1]
	v_pk_fma_f32 v[230:231], v[132:133], v[246:247], v[230:231] op_sel_hi:[0,1,1]
	v_cvt_pk_f32_fp8_sdwa v[242:243], v30 src0_sel:WORD_1
	v_cvt_pk_f32_fp8_e32 v[244:245], v31
	v_cvt_pk_f32_fp8_sdwa v[246:247], v31 src0_sel:WORD_1
	v_pk_fma_f32 v[232:233], v[132:133], v[240:241], v[232:233] op_sel_hi:[0,1,1]
	s_waitcnt vmcnt(24)
	v_cvt_pk_f32_fp8_e32 v[240:241], v32
	v_pk_fma_f32 v[234:235], v[132:133], v[242:243], v[234:235] op_sel_hi:[0,1,1]
	v_pk_fma_f32 v[236:237], v[132:133], v[244:245], v[236:237] op_sel_hi:[0,1,1]
	v_pk_fma_f32 v[238:239], v[132:133], v[246:247], v[238:239] op_sel_hi:[0,1,1]
	v_cvt_pk_f32_fp8_sdwa v[242:243], v32 src0_sel:WORD_1
	v_cvt_pk_f32_fp8_e32 v[244:245], v33
	v_cvt_pk_f32_fp8_sdwa v[246:247], v33 src0_sel:WORD_1
	v_lshlrev_b32_e32 v132, 16, v185
	v_pk_fma_f32 v[216:217], v[132:133], v[240:241], v[216:217] op_sel_hi:[0,1,1]
	v_cvt_pk_f32_fp8_e32 v[240:241], v34
	v_pk_fma_f32 v[226:227], v[132:133], v[242:243], v[226:227] op_sel_hi:[0,1,1]
	v_pk_fma_f32 v[228:229], v[132:133], v[244:245], v[228:229] op_sel_hi:[0,1,1]
	v_pk_fma_f32 v[230:231], v[132:133], v[246:247], v[230:231] op_sel_hi:[0,1,1]
	v_cvt_pk_f32_fp8_sdwa v[242:243], v34 src0_sel:WORD_1
	v_cvt_pk_f32_fp8_e32 v[244:245], v35
	v_cvt_pk_f32_fp8_sdwa v[246:247], v35 src0_sel:WORD_1
	v_pk_fma_f32 v[232:233], v[132:133], v[240:241], v[232:233] op_sel_hi:[0,1,1]
	s_waitcnt vmcnt(23)
	v_cvt_pk_f32_fp8_e32 v[240:241], v36
	v_pk_fma_f32 v[234:235], v[132:133], v[242:243], v[234:235] op_sel_hi:[0,1,1]
	v_pk_fma_f32 v[236:237], v[132:133], v[244:245], v[236:237] op_sel_hi:[0,1,1]
	v_pk_fma_f32 v[238:239], v[132:133], v[246:247], v[238:239] op_sel_hi:[0,1,1]
	v_cvt_pk_f32_fp8_sdwa v[242:243], v36 src0_sel:WORD_1
	v_cvt_pk_f32_fp8_e32 v[244:245], v37
	v_cvt_pk_f32_fp8_sdwa v[246:247], v37 src0_sel:WORD_1
	v_lshlrev_b32_e32 v132, 16, v186
	v_pk_fma_f32 v[216:217], v[132:133], v[240:241], v[216:217] op_sel_hi:[0,1,1]
	v_cvt_pk_f32_fp8_e32 v[240:241], v38
	v_pk_fma_f32 v[226:227], v[132:133], v[242:243], v[226:227] op_sel_hi:[0,1,1]
	v_pk_fma_f32 v[228:229], v[132:133], v[244:245], v[228:229] op_sel_hi:[0,1,1]
	v_pk_fma_f32 v[230:231], v[132:133], v[246:247], v[230:231] op_sel_hi:[0,1,1]
	v_cvt_pk_f32_fp8_sdwa v[242:243], v38 src0_sel:WORD_1
	v_cvt_pk_f32_fp8_e32 v[244:245], v39
	v_cvt_pk_f32_fp8_sdwa v[246:247], v39 src0_sel:WORD_1
	v_pk_fma_f32 v[232:233], v[132:133], v[240:241], v[232:233] op_sel_hi:[0,1,1]
	s_waitcnt vmcnt(22)
	v_cvt_pk_f32_fp8_e32 v[240:241], v40
	v_pk_fma_f32 v[234:235], v[132:133], v[242:243], v[234:235] op_sel_hi:[0,1,1]
	v_pk_fma_f32 v[236:237], v[132:133], v[244:245], v[236:237] op_sel_hi:[0,1,1]
	v_pk_fma_f32 v[238:239], v[132:133], v[246:247], v[238:239] op_sel_hi:[0,1,1]
	v_cvt_pk_f32_fp8_sdwa v[242:243], v40 src0_sel:WORD_1
	v_cvt_pk_f32_fp8_e32 v[244:245], v41
	v_cvt_pk_f32_fp8_sdwa v[246:247], v41 src0_sel:WORD_1
	v_lshlrev_b32_e32 v132, 16, v187
	v_pk_fma_f32 v[216:217], v[132:133], v[240:241], v[216:217] op_sel_hi:[0,1,1]
	v_cvt_pk_f32_fp8_e32 v[240:241], v42
	v_pk_fma_f32 v[226:227], v[132:133], v[242:243], v[226:227] op_sel_hi:[0,1,1]
	v_pk_fma_f32 v[228:229], v[132:133], v[244:245], v[228:229] op_sel_hi:[0,1,1]
	v_pk_fma_f32 v[230:231], v[132:133], v[246:247], v[230:231] op_sel_hi:[0,1,1]
	v_cvt_pk_f32_fp8_sdwa v[242:243], v42 src0_sel:WORD_1
	v_cvt_pk_f32_fp8_e32 v[244:245], v43
	v_cvt_pk_f32_fp8_sdwa v[246:247], v43 src0_sel:WORD_1
	v_pk_fma_f32 v[232:233], v[132:133], v[240:241], v[232:233] op_sel_hi:[0,1,1]
	s_waitcnt vmcnt(21)
; DI void up_math(const u32x4 (&W)[16], const u32 (&pj)[16], float* __restrict__ yrow, int lane) {
;     ...
;   for (int j = 0; j < 16; ++j) {
;     const float h = __uint_as_float(pj[j] << 16);
;     const f2 hh = {h, h};
; #pragma unroll
;     for (int d = 0; d < 4; ++d) {
;       f2 lo = __builtin_amdgcn_cvt_pk_f32_fp8((int)W[j][d], false);
;       f2 hi = __builtin_amdgcn_cvt_pk_f32_fp8((int)W[j][d], true);
;       y[2 * d] = lo * hh + y[2 * d];
;       y[2 * d + 1] = hi * hh + y[2 * d + 1];
;     }
;   }
	v_cvt_pk_f32_fp8_e32 v[240:241], v44
	v_pk_fma_f32 v[234:235], v[132:133], v[242:243], v[234:235] op_sel_hi:[0,1,1]
	v_pk_fma_f32 v[236:237], v[132:133], v[244:245], v[236:237] op_sel_hi:[0,1,1]
	v_pk_fma_f32 v[238:239], v[132:133], v[246:247], v[238:239] op_sel_hi:[0,1,1]
	v_cvt_pk_f32_fp8_sdwa v[242:243], v44 src0_sel:WORD_1
	v_cvt_pk_f32_fp8_e32 v[244:245], v45
	v_cvt_pk_f32_fp8_sdwa v[246:247], v45 src0_sel:WORD_1
	v_lshlrev_b32_e32 v132, 16, v190
	v_pk_fma_f32 v[216:217], v[132:133], v[240:241], v[216:217] op_sel_hi:[0,1,1]
	v_cvt_pk_f32_fp8_e32 v[240:241], v46
	v_pk_fma_f32 v[226:227], v[132:133], v[242:243], v[226:227] op_sel_hi:[0,1,1]
	v_pk_fma_f32 v[228:229], v[132:133], v[244:245], v[228:229] op_sel_hi:[0,1,1]
	v_pk_fma_f32 v[230:231], v[132:133], v[246:247], v[230:231] op_sel_hi:[0,1,1]
	v_cvt_pk_f32_fp8_sdwa v[242:243], v46 src0_sel:WORD_1
	v_cvt_pk_f32_fp8_e32 v[244:245], v47
	v_cvt_pk_f32_fp8_sdwa v[246:247], v47 src0_sel:WORD_1
	v_pk_fma_f32 v[232:233], v[132:133], v[240:241], v[232:233] op_sel_hi:[0,1,1]
	s_waitcnt vmcnt(20)
	v_cvt_pk_f32_fp8_e32 v[240:241], v48
	v_pk_fma_f32 v[234:235], v[132:133], v[242:243], v[234:235] op_sel_hi:[0,1,1]
	v_pk_fma_f32 v[236:237], v[132:133], v[244:245], v[236:237] op_sel_hi:[0,1,1]
	v_pk_fma_f32 v[238:239], v[132:133], v[246:247], v[238:239] op_sel_hi:[0,1,1]
	v_cvt_pk_f32_fp8_sdwa v[242:243], v48 src0_sel:WORD_1
	v_cvt_pk_f32_fp8_e32 v[244:245], v49
	v_cvt_pk_f32_fp8_sdwa v[246:247], v49 src0_sel:WORD_1
	v_lshlrev_b32_e32 v132, 16, v191
	v_pk_fma_f32 v[216:217], v[132:133], v[240:241], v[216:217] op_sel_hi:[0,1,1]
	v_cvt_pk_f32_fp8_e32 v[240:241], v50
	v_pk_fma_f32 v[226:227], v[132:133], v[242:243], v[226:227] op_sel_hi:[0,1,1]
	v_pk_fma_f32 v[228:229], v[132:133], v[244:245], v[228:229] op_sel_hi:[0,1,1]
	v_pk_fma_f32 v[230:231], v[132:133], v[246:247], v[230:231] op_sel_hi:[0,1,1]
	v_cvt_pk_f32_fp8_sdwa v[242:243], v50 src0_sel:WORD_1
	v_cvt_pk_f32_fp8_e32 v[244:245], v51
	v_cvt_pk_f32_fp8_sdwa v[246:247], v51 src0_sel:WORD_1
	v_pk_fma_f32 v[232:233], v[132:133], v[240:241], v[232:233] op_sel_hi:[0,1,1]
	s_waitcnt vmcnt(19)
	v_cvt_pk_f32_fp8_e32 v[240:241], v52
	v_pk_fma_f32 v[234:235], v[132:133], v[242:243], v[234:235] op_sel_hi:[0,1,1]
	v_pk_fma_f32 v[236:237], v[132:133], v[244:245], v[236:237] op_sel_hi:[0,1,1]
	v_pk_fma_f32 v[238:239], v[132:133], v[246:247], v[238:239] op_sel_hi:[0,1,1]
	v_cvt_pk_f32_fp8_sdwa v[242:243], v52 src0_sel:WORD_1
	v_cvt_pk_f32_fp8_e32 v[244:245], v53
	v_cvt_pk_f32_fp8_sdwa v[246:247], v53 src0_sel:WORD_1
	v_lshlrev_b32_e32 v132, 16, v192
	v_pk_fma_f32 v[216:217], v[132:133], v[240:241], v[216:217] op_sel_hi:[0,1,1]
	v_cvt_pk_f32_fp8_e32 v[240:241], v54
	v_pk_fma_f32 v[226:227], v[132:133], v[242:243], v[226:227] op_sel_hi:[0,1,1]
	v_pk_fma_f32 v[228:229], v[132:133], v[244:245], v[228:229] op_sel_hi:[0,1,1]
	v_pk_fma_f32 v[230:231], v[132:133], v[246:247], v[230:231] op_sel_hi:[0,1,1]
	v_cvt_pk_f32_fp8_sdwa v[242:243], v54 src0_sel:WORD_1
	v_cvt_pk_f32_fp8_e32 v[244:245], v55
	v_cvt_pk_f32_fp8_sdwa v[246:247], v55 src0_sel:WORD_1
	v_pk_fma_f32 v[232:233], v[132:133], v[240:241], v[232:233] op_sel_hi:[0,1,1]
	s_waitcnt vmcnt(18)
	v_cvt_pk_f32_fp8_e32 v[240:241], v56
	v_pk_fma_f32 v[234:235], v[132:133], v[242:243], v[234:235] op_sel_hi:[0,1,1]
	v_pk_fma_f32 v[236:237], v[132:133], v[244:245], v[236:237] op_sel_hi:[0,1,1]
	v_pk_fma_f32 v[238:239], v[132:133], v[246:247], v[238:239] op_sel_hi:[0,1,1]
	v_cvt_pk_f32_fp8_sdwa v[242:243], v56 src0_sel:WORD_1
	v_cvt_pk_f32_fp8_e32 v[244:245], v57
	v_cvt_pk_f32_fp8_sdwa v[246:247], v57 src0_sel:WORD_1
	v_lshlrev_b32_e32 v132, 16, v193
	v_pk_fma_f32 v[216:217], v[132:133], v[240:241], v[216:217] op_sel_hi:[0,1,1]
	v_cvt_pk_f32_fp8_e32 v[240:241], v58
	v_pk_fma_f32 v[226:227], v[132:133], v[242:243], v[226:227] op_sel_hi:[0,1,1]
	v_pk_fma_f32 v[228:229], v[132:133], v[244:245], v[228:229] op_sel_hi:[0,1,1]
	v_pk_fma_f32 v[230:231], v[132:133], v[246:247], v[230:231] op_sel_hi:[0,1,1]
	v_cvt_pk_f32_fp8_sdwa v[242:243], v58 src0_sel:WORD_1
	v_cvt_pk_f32_fp8_e32 v[244:245], v59
	v_cvt_pk_f32_fp8_sdwa v[246:247], v59 src0_sel:WORD_1
	v_pk_fma_f32 v[232:233], v[132:133], v[240:241], v[232:233] op_sel_hi:[0,1,1]
	s_waitcnt vmcnt(17)
	v_cvt_pk_f32_fp8_e32 v[240:241], v60
	v_pk_fma_f32 v[234:235], v[132:133], v[242:243], v[234:235] op_sel_hi:[0,1,1]
	v_pk_fma_f32 v[236:237], v[132:133], v[244:245], v[236:237] op_sel_hi:[0,1,1]
	v_pk_fma_f32 v[238:239], v[132:133], v[246:247], v[238:239] op_sel_hi:[0,1,1]
	v_cvt_pk_f32_fp8_sdwa v[242:243], v60 src0_sel:WORD_1
	v_cvt_pk_f32_fp8_e32 v[244:245], v61
	v_cvt_pk_f32_fp8_sdwa v[246:247], v61 src0_sel:WORD_1
	v_lshlrev_b32_e32 v132, 16, v194
	v_pk_fma_f32 v[216:217], v[132:133], v[240:241], v[216:217] op_sel_hi:[0,1,1]
	v_cvt_pk_f32_fp8_e32 v[240:241], v62
	v_pk_fma_f32 v[226:227], v[132:133], v[242:243], v[226:227] op_sel_hi:[0,1,1]
	v_pk_fma_f32 v[228:229], v[132:133], v[244:245], v[228:229] op_sel_hi:[0,1,1]
	v_pk_fma_f32 v[230:231], v[132:133], v[246:247], v[230:231] op_sel_hi:[0,1,1]
	v_cvt_pk_f32_fp8_sdwa v[242:243], v62 src0_sel:WORD_1
	v_cvt_pk_f32_fp8_e32 v[244:245], v63
	v_cvt_pk_f32_fp8_sdwa v[246:247], v63 src0_sel:WORD_1
	v_pk_fma_f32 v[232:233], v[132:133], v[240:241], v[232:233] op_sel_hi:[0,1,1]
	s_waitcnt vmcnt(16)
; DI void up_issue(u32x4 (&W)[16], u32 (&pj)[16], const u32* pl, const unsigned char* wbase, int grp) {
; #pragma unroll
;   for (int j = 0; j < 16; ++j) {
;     pj[j] = pl[8 * j + grp];
;     W[j] = *(const u32x4*)(wbase + (size_t)(pj[j] >> 16) * 1024);
;   }
; DI void up_math(const u32x4 (&W)[16], const u32 (&pj)[16], float* __restrict__ yrow, int lane) {
;     ...
;   for (int j = 0; j < 16; ++j) {
;     const float h = __uint_as_float(pj[j] << 16);
;     const f2 hh = {h, h};
; #pragma unroll
;     for (int d = 0; d < 4; ++d) {
;       f2 lo = __builtin_amdgcn_cvt_pk_f32_fp8((int)W[j][d], false);
;       f2 hi = __builtin_amdgcn_cvt_pk_f32_fp8((int)W[j][d], true);
;       y[2 * d] = lo * hh + y[2 * d];
;       y[2 * d + 1] = hi * hh + y[2 * d + 1];
;     }
;   }
;   const bool b5 = lane & 32, b4 = lane & 16, b3 = lane & 8;
;   f2 q4[4];
; #pragma unroll
;   for (int i = 0; i < 4; ++i) {
;     f2 snd = b5 ? y[i] : y[i + 4]; f2 kp = b5 ? y[i + 4] : y[i];
;     q4[i] = f2{kp.x + __shfl_xor(snd.x, 32), kp.y + __shfl_xor(snd.y, 32)};
;   }
;   f2 r2[2];
; #pragma unroll
;   for (int i = 0; i < 2; ++i) {
;     f2 snd = b4 ? q4[i] : q4[i + 2]; f2 kp = b4 ? q4[i + 2] : q4[i];
;     r2[i] = f2{kp.x + __shfl_xor(snd.x, 16), kp.y + __shfl_xor(snd.y, 16)};
;   }
;   f2 a;
;   { f2 snd = b3 ? r2[0] : r2[1]; f2 kp = b3 ? r2[1] : r2[0]; a = f2{kp.x + __shfl_xor(snd.x, 8), kp.y + __shfl_xor(snd.y, 8)}; }
;   const int ci = (b5 ? 4 : 0) + (b4 ? 2 : 0) + (b3 ? 1 : 0);
;   *(float2*)(yrow + (lane & 7) * 16 + 2 * ci) = make_float2(a.x, a.y);
	v_cvt_pk_f32_fp8_e32 v[240:241], v64
	v_pk_fma_f32 v[234:235], v[132:133], v[242:243], v[234:235] op_sel_hi:[0,1,1]
	v_pk_fma_f32 v[236:237], v[132:133], v[244:245], v[236:237] op_sel_hi:[0,1,1]
	v_pk_fma_f32 v[238:239], v[132:133], v[246:247], v[238:239] op_sel_hi:[0,1,1]
	v_cvt_pk_f32_fp8_sdwa v[242:243], v64 src0_sel:WORD_1
	v_cvt_pk_f32_fp8_e32 v[244:245], v65
	v_cvt_pk_f32_fp8_sdwa v[246:247], v65 src0_sel:WORD_1
	v_lshlrev_b32_e32 v132, 16, v195
	v_pk_fma_f32 v[216:217], v[132:133], v[240:241], v[216:217] op_sel_hi:[0,1,1]
	v_cvt_pk_f32_fp8_e32 v[240:241], v66
	v_pk_fma_f32 v[226:227], v[132:133], v[242:243], v[226:227] op_sel_hi:[0,1,1]
	v_pk_fma_f32 v[228:229], v[132:133], v[244:245], v[228:229] op_sel_hi:[0,1,1]
	v_pk_fma_f32 v[230:231], v[132:133], v[246:247], v[230:231] op_sel_hi:[0,1,1]
	v_cvt_pk_f32_fp8_sdwa v[242:243], v66 src0_sel:WORD_1
	v_cvt_pk_f32_fp8_e32 v[244:245], v67
	v_cvt_pk_f32_fp8_sdwa v[246:247], v67 src0_sel:WORD_1
	v_pk_fma_f32 v[232:233], v[132:133], v[240:241], v[232:233] op_sel_hi:[0,1,1]
	v_pk_fma_f32 v[234:235], v[132:133], v[242:243], v[234:235] op_sel_hi:[0,1,1]
	v_pk_fma_f32 v[236:237], v[132:133], v[244:245], v[236:237] op_sel_hi:[0,1,1]
	v_pk_fma_f32 v[238:239], v[132:133], v[246:247], v[238:239] op_sel_hi:[0,1,1]
	s_nop 1
	v_permlane32_swap_b32_e32 v216, v232
	v_permlane32_swap_b32_e32 v217, v233
	v_permlane32_swap_b32_e32 v228, v236
	v_permlane32_swap_b32_e32 v229, v237
	v_permlane32_swap_b32_e32 v226, v234
	v_permlane32_swap_b32_e32 v227, v235
	v_permlane32_swap_b32_e32 v230, v238
	v_permlane32_swap_b32_e32 v231, v239
	v_pk_add_f32 v[216:217], v[216:217], v[232:233]
	v_pk_add_f32 v[228:229], v[228:229], v[236:237]
	v_pk_add_f32 v[226:227], v[226:227], v[234:235]
	v_pk_add_f32 v[230:231], v[230:231], v[238:239]
	s_nop 1
	v_permlane16_swap_b32_e32 v216, v228
	v_permlane16_swap_b32_e32 v217, v229
	v_permlane16_swap_b32_e32 v226, v230
	v_permlane16_swap_b32_e32 v227, v231
	v_pk_add_f32 v[216:217], v[216:217], v[228:229]
	v_pk_add_f32 v[226:227], v[226:227], v[230:231]
	s_nop 0
	v_cndmask_b32_e64 v132, v217, v227, s[10:11]
	v_cndmask_b32_e64 v147, v216, v226, s[10:11]
	ds_bpermute_b32 v228, v143, v147
	ds_bpermute_b32 v229, v143, v132
	v_cndmask_b32_e64 v217, v227, v217, s[10:11]
	v_cndmask_b32_e64 v216, v226, v216, s[10:11]
	s_waitcnt lgkmcnt(0)
	v_pk_add_f32 v[216:217], v[216:217], v[228:229]
	global_store_dwordx2 v[188:189], v[216:217], off
	s_cmp_gt_u32 s36, 13
	s_cselect_b64 s[28:29], -1, 0
	s_and_b64 vcc, exec, s[28:29]
	s_cbranch_vccnz .LBB0_1649
	ds_read2_b32 v[178:179], v145 offset0:128 offset1:136
	ds_read2_b32 v[180:181], v145 offset0:144 offset1:152
	s_waitcnt lgkmcnt(1)
	v_lshlrev_b32_sdwa v132, v215, v178 dst_sel:DWORD dst_unused:UNUSED_PAD src0_sel:DWORD src1_sel:WORD_1
	v_lshl_add_u64 v[4:5], v[174:175], 0, v[132:133]
	v_lshlrev_b32_sdwa v132, v215, v179 dst_sel:DWORD dst_unused:UNUSED_PAD src0_sel:DWORD src1_sel:WORD_1
	v_lshl_add_u64 v[8:9], v[174:175], 0, v[132:133]
	s_waitcnt lgkmcnt(0)
	v_lshlrev_b32_sdwa v132, v215, v180 dst_sel:DWORD dst_unused:UNUSED_PAD src0_sel:DWORD src1_sel:WORD_1
	global_load_dwordx4 v[4:7], v[4:5], off
	s_nop 0
	global_load_dwordx4 v[8:11], v[8:9], off
	v_lshl_add_u64 v[12:13], v[174:175], 0, v[132:133]
	ds_read2_b32 v[182:183], v145 offset0:160 offset1:168
	v_lshlrev_b32_sdwa v132, v215, v181 dst_sel:DWORD dst_unused:UNUSED_PAD src0_sel:DWORD src1_sel:WORD_1
	v_lshl_add_u64 v[16:17], v[174:175], 0, v[132:133]
	global_load_dwordx4 v[12:15], v[12:13], off
	s_nop 0
	global_load_dwordx4 v[16:19], v[16:17], off
	ds_read2_b32 v[184:185], v145 offset0:176 offset1:184
	s_waitcnt lgkmcnt(1)
	v_lshlrev_b32_sdwa v132, v215, v182 dst_sel:DWORD dst_unused:UNUSED_PAD src0_sel:DWORD src1_sel:WORD_1
	v_lshl_add_u64 v[20:21], v[174:175], 0, v[132:133]
	v_lshlrev_b32_sdwa v132, v215, v183 dst_sel:DWORD dst_unused:UNUSED_PAD src0_sel:DWORD src1_sel:WORD_1
	v_lshl_add_u64 v[24:25], v[174:175], 0, v[132:133]
	s_waitcnt lgkmcnt(0)
	v_lshlrev_b32_sdwa v132, v215, v184 dst_sel:DWORD dst_unused:UNUSED_PAD src0_sel:DWORD src1_sel:WORD_1
	global_load_dwordx4 v[20:23], v[20:21], off
	s_nop 0
	global_load_dwordx4 v[24:27], v[24:25], off
	v_lshl_add_u64 v[28:29], v[174:175], 0, v[132:133]
	ds_read2_b32 v[186:187], v145 offset0:192 offset1:200
	v_lshlrev_b32_sdwa v132, v215, v185 dst_sel:DWORD dst_unused:UNUSED_PAD src0_sel:DWORD src1_sel:WORD_1
	v_lshl_add_u64 v[32:33], v[174:175], 0, v[132:133]
	global_load_dwordx4 v[28:31], v[28:29], off
	s_nop 0
	global_load_dwordx4 v[32:35], v[32:33], off
	ds_read2_b32 v[190:191], v145 offset0:208 offset1:216
	s_waitcnt lgkmcnt(1)
	v_lshlrev_b32_sdwa v132, v215, v186 dst_sel:DWORD dst_unused:UNUSED_PAD src0_sel:DWORD src1_sel:WORD_1
	v_lshl_add_u64 v[36:37], v[174:175], 0, v[132:133]
	v_lshlrev_b32_sdwa v132, v215, v187 dst_sel:DWORD dst_unused:UNUSED_PAD src0_sel:DWORD src1_sel:WORD_1
	v_lshl_add_u64 v[40:41], v[174:175], 0, v[132:133]
	s_waitcnt lgkmcnt(0)
	v_lshlrev_b32_sdwa v132, v215, v190 dst_sel:DWORD dst_unused:UNUSED_PAD src0_sel:DWORD src1_sel:WORD_1
	global_load_dwordx4 v[36:39], v[36:37], off
	s_nop 0
	global_load_dwordx4 v[40:43], v[40:41], off
	v_lshl_add_u64 v[44:45], v[174:175], 0, v[132:133]
	ds_read2_b32 v[192:193], v145 offset0:224 offset1:232
	v_lshlrev_b32_sdwa v132, v215, v191 dst_sel:DWORD dst_unused:UNUSED_PAD src0_sel:DWORD src1_sel:WORD_1
	v_lshl_add_u64 v[48:49], v[174:175], 0, v[132:133]
	global_load_dwordx4 v[44:47], v[44:45], off
	s_nop 0
	global_load_dwordx4 v[48:51], v[48:49], off
	ds_read2_b32 v[194:195], v145 offset0:240 offset1:248
	s_waitcnt lgkmcnt(1)
	v_lshlrev_b32_sdwa v132, v215, v192 dst_sel:DWORD dst_unused:UNUSED_PAD src0_sel:DWORD src1_sel:WORD_1
	v_lshl_add_u64 v[52:53], v[174:175], 0, v[132:133]
	v_lshlrev_b32_sdwa v132, v215, v193 dst_sel:DWORD dst_unused:UNUSED_PAD src0_sel:DWORD src1_sel:WORD_1
	v_lshl_add_u64 v[56:57], v[174:175], 0, v[132:133]
	s_waitcnt lgkmcnt(0)
	v_lshlrev_b32_sdwa v132, v215, v194 dst_sel:DWORD dst_unused:UNUSED_PAD src0_sel:DWORD src1_sel:WORD_1
	v_lshl_add_u64 v[60:61], v[174:175], 0, v[132:133]
	v_lshlrev_b32_sdwa v132, v215, v195 dst_sel:DWORD dst_unused:UNUSED_PAD src0_sel:DWORD src1_sel:WORD_1
	v_lshl_add_u64 v[64:65], v[174:175], 0, v[132:133]
	global_load_dwordx4 v[52:55], v[52:53], off
	s_nop 0
	global_load_dwordx4 v[56:59], v[56:57], off
	s_nop 0
	global_load_dwordx4 v[60:63], v[60:61], off
	s_nop 0
	global_load_dwordx4 v[64:67], v[64:65], off
	s_branch .LBB0_1649
